# v32 plus one static s_setprio 1 for waves 4-7 at kernel entry, the 80 per-cluster priority flips of the GEMM loops deleted
# speedup vs baseline: 1.0018x; 1.0018x over previous
.LBB0_11:
	s_or_b64 exec, exec, s[4:5]
	v_and_b32_e32 v232, 63, v0
	s_mov_b64 s[6:7], s[0:1]
	v_mov_b32_e32 v82, v0
	s_mov_b64 s[8:9], s[44:45]
	v_mov_b32_e32 v4, v232
	s_mov_b64 s[4:5], s[46:47]
	s_load_dwordx8 s[8:15], s[6:7], 0x40
	v_readfirstlane_b32 s3, v0
	s_nop 3
	s_lshr_b32 s3, s3, 6
	s_cmp_ge_u32 s3, 4
	s_cbranch_scc0 .Lprio_done
	s_setprio 1
.Lprio_done:
	s_movk_i32 s3, 0x800
	v_cmp_gt_i32_e32 vcc, s3, v82
	s_and_saveexec_b64 s[6:7], vcc
	s_cbranch_execz .LBB0_14
	s_waitcnt lgkmcnt(0)
	v_mov_b32_e32 v2, s8
	v_mov_b32_e32 v3, s9
	v_lshl_add_u32 v5, v82, 2, 0
	v_ashrrev_i32_e32 v83, 31, v82
	v_add_u32_e32 v1, 0xfffffe00, v82
	v_add_u32_e32 v5, 0x10000, v5
	v_lshl_add_u64 v[2:3], v[82:83], 2, v[2:3]
	s_mov_b64 s[8:9], 0
	s_mov_b64 s[16:17], 0x800
	s_movk_i32 s3, 0x5ff

.LBB0_170:
	s_add_u32 s36, s12, 0xfff80080
	s_addc_u32 s37, s13, -1
	s_add_i32 s87, 0, 0x10000
	s_cmp_eq_u32 s86, 28
	s_cselect_b32 s39, s11, s37
	s_cselect_b32 s38, s27, s36
	v_add_u32_e32 v82, s87, v207
	s_cselect_b32 s37, s25, s85
	s_cselect_b32 s36, s35, s70
	s_add_i32 s90, 0, 0x14000
	ds_read_b128 v[132:135], v82
	ds_read_b128 v[136:139], v82 offset:1024
	ds_read_b128 v[140:143], v82 offset:2048
	ds_read_b128 v[144:147], v82 offset:3072
	v_add_u32_e32 v82, s90, v207
	ds_read_b128 v[148:151], v82
	ds_read_b128 v[152:155], v82 offset:1024
	ds_read_b128 v[156:159], v82 offset:2048
	ds_read_b128 v[160:163], v82 offset:3072
	v_lshl_add_u64 v[204:205], s[12:13], 0, v[190:191]
	s_add_i32 m0, s41, 0xc000
	ds_read_b128 v[164:167], v208
	ds_read_b128 v[168:171], v208 offset:1024
	ds_read_b128 v[192:195], v208 offset:2048
	ds_read_b128 v[196:199], v208 offset:3072
	ds_read_b128 v[200:203], v208 offset:4096
	ds_read_b128 v[210:213], v208 offset:5120
	ds_read_b128 v[214:217], v208 offset:6144
	ds_read_b128 v[218:221], v208 offset:7168
	global_load_lds_dwordx4 v[204:205], off
	v_lshl_add_u64 v[204:205], s[12:13], 0, v[188:189]
	s_add_i32 m0, s41, 0xe000
	s_nop 0
	global_load_lds_dwordx4 v[204:205], off
	s_waitcnt vmcnt(8)
	s_waitcnt lgkmcnt(0)
	s_barrier
	s_waitcnt lgkmcnt(0)
	v_mfma_f32_16x16x32_bf16 v[128:131], v[132:135], v[164:167], v[128:131]
	v_mfma_f32_16x16x32_bf16 v[124:127], v[140:143], v[164:167], v[124:127]
	v_mfma_f32_16x16x32_bf16 v[112:115], v[132:135], v[192:195], v[112:115]
	v_mfma_f32_16x16x32_bf16 v[108:111], v[140:143], v[192:195], v[108:111]
	v_mfma_f32_16x16x32_bf16 v[96:99], v[132:135], v[200:203], v[96:99]
	v_mfma_f32_16x16x32_bf16 v[92:95], v[140:143], v[200:203], v[92:95]
	v_mfma_f32_16x16x32_bf16 v[78:81], v[132:135], v[214:217], v[78:81]
	v_mfma_f32_16x16x32_bf16 v[74:77], v[140:143], v[214:217], v[74:77]
	v_mfma_f32_16x16x32_bf16 v[128:131], v[136:139], v[168:171], v[128:131]
	v_mfma_f32_16x16x32_bf16 v[124:127], v[144:147], v[168:171], v[124:127]
	v_mfma_f32_16x16x32_bf16 v[112:115], v[136:139], v[196:199], v[112:115]
	v_mfma_f32_16x16x32_bf16 v[108:111], v[144:147], v[196:199], v[108:111]
	v_mfma_f32_16x16x32_bf16 v[96:99], v[136:139], v[210:213], v[96:99]
	v_mfma_f32_16x16x32_bf16 v[92:95], v[144:147], v[210:213], v[92:95]
	v_mfma_f32_16x16x32_bf16 v[78:81], v[136:139], v[218:221], v[78:81]
	v_mfma_f32_16x16x32_bf16 v[74:77], v[144:147], v[218:221], v[74:77]
	v_mfma_f32_16x16x32_bf16 v[120:123], v[148:151], v[164:167], v[120:123]
	v_mfma_f32_16x16x32_bf16 v[116:119], v[156:159], v[164:167], v[116:119]
	v_mfma_f32_16x16x32_bf16 v[104:107], v[148:151], v[192:195], v[104:107]
	v_mfma_f32_16x16x32_bf16 v[100:103], v[156:159], v[192:195], v[100:103]
	v_mfma_f32_16x16x32_bf16 v[88:91], v[148:151], v[200:203], v[88:91]
	v_mfma_f32_16x16x32_bf16 v[84:87], v[156:159], v[200:203], v[84:87]
	v_mfma_f32_16x16x32_bf16 v[70:73], v[148:151], v[214:217], v[70:73]
	v_mfma_f32_16x16x32_bf16 v[66:69], v[156:159], v[214:217], v[66:69]
	v_mfma_f32_16x16x32_bf16 v[120:123], v[152:155], v[168:171], v[120:123]
	v_mfma_f32_16x16x32_bf16 v[116:119], v[160:163], v[168:171], v[116:119]
	v_mfma_f32_16x16x32_bf16 v[104:107], v[152:155], v[196:199], v[104:107]
	v_mfma_f32_16x16x32_bf16 v[100:103], v[160:163], v[196:199], v[100:103]
	v_mfma_f32_16x16x32_bf16 v[88:91], v[152:155], v[210:213], v[88:91]
	v_mfma_f32_16x16x32_bf16 v[84:87], v[160:163], v[210:213], v[84:87]
	v_mfma_f32_16x16x32_bf16 v[70:73], v[152:155], v[218:221], v[70:73]
	v_mfma_f32_16x16x32_bf16 v[66:69], v[160:163], v[218:221], v[66:69]
	s_barrier
	s_add_i32 s87, s87, s40
	v_lshl_add_u64 v[204:205], s[36:37], 0, v[174:175]
	s_mov_b32 m0, s87
	ds_read_b128 v[164:167], v208 offset:16384
	ds_read_b128 v[168:171], v208 offset:17408
	ds_read_b128 v[192:195], v208 offset:18432
	ds_read_b128 v[196:199], v208 offset:19456
	ds_read_b128 v[200:203], v208 offset:20480
	ds_read_b128 v[210:213], v208 offset:21504
	ds_read_b128 v[214:217], v208 offset:22528
	ds_read_b128 v[218:221], v208 offset:23552
	global_load_lds_dwordx4 v[204:205], off
	s_add_i32 m0, s87, 0x2000
	s_add_u32 s88, s36, 0x80000
	v_lshl_add_u64 v[222:223], s[36:37], 0, v[178:179]
	s_addc_u32 s89, s37, 0
	s_add_i32 s87, s90, s40
	global_load_lds_dwordx4 v[222:223], off
	v_lshl_add_u64 v[224:225], s[88:89], 0, v[174:175]
	s_mov_b32 m0, s87
	v_lshl_add_u64 v[234:235], s[38:39], 0, v[176:177]
	global_load_lds_dwordx4 v[224:225], off
	v_lshl_add_u64 v[224:225], s[88:89], 0, v[178:179]
	s_add_i32 m0, s87, 0x2000
	s_nop 0
	global_load_lds_dwordx4 v[224:225], off
	v_lshl_add_u64 v[224:225], s[38:39], 0, v[172:173]
	s_mov_b32 m0, s41
	s_nop 0
	global_load_lds_dwordx4 v[224:225], off
	s_mov_b32 m0, s58
	s_nop 0
	global_load_lds_dwordx4 v[234:235], off
	s_waitcnt vmcnt(8)
	s_waitcnt lgkmcnt(0)
	s_barrier
	s_waitcnt lgkmcnt(0)
	v_mfma_f32_16x16x32_bf16 v[62:65], v[132:135], v[164:167], v[62:65]
	v_mfma_f32_16x16x32_bf16 v[58:61], v[140:143], v[164:167], v[58:61]
	v_mfma_f32_16x16x32_bf16 v[46:49], v[132:135], v[192:195], v[46:49]
	v_mfma_f32_16x16x32_bf16 v[42:45], v[140:143], v[192:195], v[42:45]
	v_mfma_f32_16x16x32_bf16 v[30:33], v[132:135], v[200:203], v[30:33]
	v_mfma_f32_16x16x32_bf16 v[26:29], v[140:143], v[200:203], v[26:29]
	v_mfma_f32_16x16x32_bf16 v[14:17], v[132:135], v[214:217], v[14:17]
	v_mfma_f32_16x16x32_bf16 v[10:13], v[140:143], v[214:217], v[10:13]
	v_mfma_f32_16x16x32_bf16 v[62:65], v[136:139], v[168:171], v[62:65]
	v_mfma_f32_16x16x32_bf16 v[58:61], v[144:147], v[168:171], v[58:61]
	v_mfma_f32_16x16x32_bf16 v[46:49], v[136:139], v[196:199], v[46:49]
	v_mfma_f32_16x16x32_bf16 v[42:45], v[144:147], v[196:199], v[42:45]
	v_mfma_f32_16x16x32_bf16 v[30:33], v[136:139], v[210:213], v[30:33]
	v_mfma_f32_16x16x32_bf16 v[26:29], v[144:147], v[210:213], v[26:29]
	v_mfma_f32_16x16x32_bf16 v[14:17], v[136:139], v[218:221], v[14:17]
	v_mfma_f32_16x16x32_bf16 v[10:13], v[144:147], v[218:221], v[10:13]
	v_mfma_f32_16x16x32_bf16 v[54:57], v[148:151], v[164:167], v[54:57]
	v_mfma_f32_16x16x32_bf16 v[50:53], v[156:159], v[164:167], v[50:53]
	v_mfma_f32_16x16x32_bf16 v[38:41], v[148:151], v[192:195], v[38:41]
	v_mfma_f32_16x16x32_bf16 v[34:37], v[156:159], v[192:195], v[34:37]
	v_mfma_f32_16x16x32_bf16 v[22:25], v[148:151], v[200:203], v[22:25]
	v_mfma_f32_16x16x32_bf16 v[18:21], v[156:159], v[200:203], v[18:21]
	v_mfma_f32_16x16x32_bf16 v[6:9], v[148:151], v[214:217], v[6:9]
	v_mfma_f32_16x16x32_bf16 v[2:5], v[156:159], v[214:217], v[2:5]
	v_mfma_f32_16x16x32_bf16 v[54:57], v[152:155], v[168:171], v[54:57]
	v_mfma_f32_16x16x32_bf16 v[50:53], v[160:163], v[168:171], v[50:53]
	v_mfma_f32_16x16x32_bf16 v[38:41], v[152:155], v[196:199], v[38:41]
	v_mfma_f32_16x16x32_bf16 v[34:37], v[160:163], v[196:199], v[34:37]
	v_mfma_f32_16x16x32_bf16 v[22:25], v[152:155], v[210:213], v[22:25]
	v_mfma_f32_16x16x32_bf16 v[18:21], v[160:163], v[210:213], v[18:21]
	v_mfma_f32_16x16x32_bf16 v[6:9], v[152:155], v[218:221], v[6:9]
	v_mfma_f32_16x16x32_bf16 v[2:5], v[160:163], v[218:221], v[2:5]
	s_barrier
	s_add_i32 s87, 0, 0x18000
	v_add_u32_e32 v82, s87, v207
	s_add_i32 s88, 0, 0x1c000
	ds_read_b128 v[132:135], v82
	ds_read_b128 v[136:139], v82 offset:1024
	ds_read_b128 v[140:143], v82 offset:2048
	ds_read_b128 v[144:147], v82 offset:3072
	v_add_u32_e32 v82, s88, v207
	ds_read_b128 v[148:151], v82
	ds_read_b128 v[152:155], v82 offset:1024
	ds_read_b128 v[156:159], v82 offset:2048
	ds_read_b128 v[160:163], v82 offset:3072
	s_add_u32 s38, s38, 0x80000
	s_addc_u32 s39, s39, 0
	s_mov_b32 m0, s59
	v_lshl_add_u64 v[236:237], s[38:39], 0, v[172:173]
	ds_read_b128 v[164:167], v208 offset:32768
	ds_read_b128 v[168:171], v208 offset:33792
	ds_read_b128 v[192:195], v208 offset:34816
	ds_read_b128 v[196:199], v208 offset:35840
	ds_read_b128 v[200:203], v208 offset:36864
	ds_read_b128 v[210:213], v208 offset:37888
	ds_read_b128 v[214:217], v208 offset:38912
	ds_read_b128 v[218:221], v208 offset:39936
	global_load_lds_dwordx4 v[236:237], off
	v_lshl_add_u64 v[236:237], s[38:39], 0, v[176:177]
	s_mov_b32 m0, s60
	s_nop 0
	global_load_lds_dwordx4 v[236:237], off
	s_waitcnt vmcnt(8)
	s_waitcnt lgkmcnt(0)
	s_barrier
	s_waitcnt lgkmcnt(0)
	v_mfma_f32_16x16x32_bf16 v[128:131], v[132:135], v[164:167], v[128:131]
	v_mfma_f32_16x16x32_bf16 v[124:127], v[140:143], v[164:167], v[124:127]
	v_mfma_f32_16x16x32_bf16 v[112:115], v[132:135], v[192:195], v[112:115]
	v_mfma_f32_16x16x32_bf16 v[108:111], v[140:143], v[192:195], v[108:111]
	v_mfma_f32_16x16x32_bf16 v[96:99], v[132:135], v[200:203], v[96:99]
	v_mfma_f32_16x16x32_bf16 v[92:95], v[140:143], v[200:203], v[92:95]
	v_mfma_f32_16x16x32_bf16 v[78:81], v[132:135], v[214:217], v[78:81]
	v_mfma_f32_16x16x32_bf16 v[74:77], v[140:143], v[214:217], v[74:77]
	v_mfma_f32_16x16x32_bf16 v[128:131], v[136:139], v[168:171], v[128:131]
	v_mfma_f32_16x16x32_bf16 v[124:127], v[144:147], v[168:171], v[124:127]
	v_mfma_f32_16x16x32_bf16 v[112:115], v[136:139], v[196:199], v[112:115]
	v_mfma_f32_16x16x32_bf16 v[108:111], v[144:147], v[196:199], v[108:111]
	v_mfma_f32_16x16x32_bf16 v[96:99], v[136:139], v[210:213], v[96:99]
	v_mfma_f32_16x16x32_bf16 v[92:95], v[144:147], v[210:213], v[92:95]
	v_mfma_f32_16x16x32_bf16 v[78:81], v[136:139], v[218:221], v[78:81]
	v_mfma_f32_16x16x32_bf16 v[74:77], v[144:147], v[218:221], v[74:77]
	v_mfma_f32_16x16x32_bf16 v[120:123], v[148:151], v[164:167], v[120:123]
	v_mfma_f32_16x16x32_bf16 v[116:119], v[156:159], v[164:167], v[116:119]
	v_mfma_f32_16x16x32_bf16 v[104:107], v[148:151], v[192:195], v[104:107]
	v_mfma_f32_16x16x32_bf16 v[100:103], v[156:159], v[192:195], v[100:103]
	v_mfma_f32_16x16x32_bf16 v[88:91], v[148:151], v[200:203], v[88:91]
	v_mfma_f32_16x16x32_bf16 v[84:87], v[156:159], v[200:203], v[84:87]
	v_mfma_f32_16x16x32_bf16 v[70:73], v[148:151], v[214:217], v[70:73]
	v_mfma_f32_16x16x32_bf16 v[66:69], v[156:159], v[214:217], v[66:69]
	v_mfma_f32_16x16x32_bf16 v[120:123], v[152:155], v[168:171], v[120:123]
	v_mfma_f32_16x16x32_bf16 v[116:119], v[160:163], v[168:171], v[116:119]
	v_mfma_f32_16x16x32_bf16 v[104:107], v[152:155], v[196:199], v[104:107]
	v_mfma_f32_16x16x32_bf16 v[100:103], v[160:163], v[196:199], v[100:103]
	v_mfma_f32_16x16x32_bf16 v[88:91], v[152:155], v[210:213], v[88:91]
	v_mfma_f32_16x16x32_bf16 v[84:87], v[160:163], v[210:213], v[84:87]
	v_mfma_f32_16x16x32_bf16 v[70:73], v[152:155], v[218:221], v[70:73]
	v_mfma_f32_16x16x32_bf16 v[66:69], v[160:163], v[218:221], v[66:69]
	s_barrier
	s_add_i32 s38, s87, s40
	v_lshl_add_u64 v[204:205], v[204:205], 0, s[68:69]
	s_mov_b32 m0, s38
	ds_read_b128 v[164:167], v208 offset:49152
	ds_read_b128 v[168:171], v208 offset:50176
	ds_read_b128 v[192:195], v208 offset:51200
	ds_read_b128 v[196:199], v208 offset:52224
	ds_read_b128 v[200:203], v208 offset:53248
	ds_read_b128 v[210:213], v208 offset:54272
	ds_read_b128 v[214:217], v208 offset:55296
	ds_read_b128 v[218:221], v208 offset:56320
	global_load_lds_dwordx4 v[204:205], off
	s_add_i32 m0, s38, 0x2000
	s_add_u32 s36, s36, 0x80080
	v_lshl_add_u64 v[204:205], v[222:223], 0, s[68:69]
	s_addc_u32 s37, s37, 0
	s_add_i32 s38, s88, s40
	global_load_lds_dwordx4 v[204:205], off
	v_lshl_add_u64 v[204:205], s[36:37], 0, v[174:175]
	s_mov_b32 m0, s38
	s_nop 0
	global_load_lds_dwordx4 v[204:205], off
	v_lshl_add_u64 v[204:205], s[36:37], 0, v[178:179]
	s_add_i32 m0, s38, 0x2000
	s_nop 0
	global_load_lds_dwordx4 v[204:205], off
	v_lshl_add_u64 v[204:205], v[224:225], 0, s[68:69]
	s_mov_b32 m0, s74
	s_nop 0
	global_load_lds_dwordx4 v[204:205], off
	v_lshl_add_u64 v[204:205], v[234:235], 0, s[68:69]
	s_mov_b32 m0, s75
	s_nop 0
	global_load_lds_dwordx4 v[204:205], off
	s_waitcnt vmcnt(8)
	s_waitcnt lgkmcnt(0)
	s_barrier
	s_waitcnt lgkmcnt(0)
	v_mfma_f32_16x16x32_bf16 v[62:65], v[132:135], v[164:167], v[62:65]
	v_mfma_f32_16x16x32_bf16 v[58:61], v[140:143], v[164:167], v[58:61]
	v_mfma_f32_16x16x32_bf16 v[46:49], v[132:135], v[192:195], v[46:49]
	v_mfma_f32_16x16x32_bf16 v[42:45], v[140:143], v[192:195], v[42:45]
	v_mfma_f32_16x16x32_bf16 v[30:33], v[132:135], v[200:203], v[30:33]
	v_mfma_f32_16x16x32_bf16 v[26:29], v[140:143], v[200:203], v[26:29]
	v_mfma_f32_16x16x32_bf16 v[14:17], v[132:135], v[214:217], v[14:17]
	v_mfma_f32_16x16x32_bf16 v[10:13], v[140:143], v[214:217], v[10:13]
	v_mfma_f32_16x16x32_bf16 v[62:65], v[136:139], v[168:171], v[62:65]
	v_mfma_f32_16x16x32_bf16 v[58:61], v[144:147], v[168:171], v[58:61]
	v_mfma_f32_16x16x32_bf16 v[46:49], v[136:139], v[196:199], v[46:49]
	v_mfma_f32_16x16x32_bf16 v[42:45], v[144:147], v[196:199], v[42:45]
	v_mfma_f32_16x16x32_bf16 v[30:33], v[136:139], v[210:213], v[30:33]
	v_mfma_f32_16x16x32_bf16 v[26:29], v[144:147], v[210:213], v[26:29]
	v_mfma_f32_16x16x32_bf16 v[14:17], v[136:139], v[218:221], v[14:17]
	v_mfma_f32_16x16x32_bf16 v[10:13], v[144:147], v[218:221], v[10:13]
	v_mfma_f32_16x16x32_bf16 v[54:57], v[148:151], v[164:167], v[54:57]
	v_mfma_f32_16x16x32_bf16 v[50:53], v[156:159], v[164:167], v[50:53]
	v_mfma_f32_16x16x32_bf16 v[38:41], v[148:151], v[192:195], v[38:41]
	v_mfma_f32_16x16x32_bf16 v[34:37], v[156:159], v[192:195], v[34:37]
	v_mfma_f32_16x16x32_bf16 v[22:25], v[148:151], v[200:203], v[22:25]
	v_mfma_f32_16x16x32_bf16 v[18:21], v[156:159], v[200:203], v[18:21]
	v_mfma_f32_16x16x32_bf16 v[6:9], v[148:151], v[214:217], v[6:9]
	v_mfma_f32_16x16x32_bf16 v[2:5], v[156:159], v[214:217], v[2:5]
	v_mfma_f32_16x16x32_bf16 v[54:57], v[152:155], v[168:171], v[54:57]
	v_mfma_f32_16x16x32_bf16 v[50:53], v[160:163], v[168:171], v[50:53]
	v_mfma_f32_16x16x32_bf16 v[38:41], v[152:155], v[196:199], v[38:41]
	v_mfma_f32_16x16x32_bf16 v[34:37], v[160:163], v[196:199], v[34:37]
	v_mfma_f32_16x16x32_bf16 v[22:25], v[152:155], v[210:213], v[22:25]
	v_mfma_f32_16x16x32_bf16 v[18:21], v[160:163], v[210:213], v[18:21]
	v_mfma_f32_16x16x32_bf16 v[6:9], v[152:155], v[218:221], v[6:9]
	v_mfma_f32_16x16x32_bf16 v[2:5], v[160:163], v[218:221], v[2:5]
	s_barrier
	s_add_i32 s86, s86, 2
	s_add_u32 s70, s70, 0x100
	s_addc_u32 s85, s85, 0
	s_add_u32 s12, s12, 0x100
	s_addc_u32 s13, s13, 0
	s_cmp_gt_u32 s86, 29
	s_cbranch_scc0 .LBB0_170
	s_and_b64 vcc, exec, s[16:17]
	s_cbranch_vccz .LBB0_173
	s_barrier

.LBB0_389:
	s_add_u32 s16, s14, 0xec1b100
	s_addc_u32 s17, s15, 0
	s_add_u32 s35, s14, s30
	s_addc_u32 s36, s15, s31
	s_add_i32 s37, 0, 0x10000
	s_cmp_eq_u32 s34, 28
	s_cselect_b32 s19, s13, s17
	s_cselect_b32 s18, s12, s16
	s_cselect_b32 s17, s9, s36
	s_cselect_b32 s16, s8, s35
	s_add_i32 s35, 0, 0x14000
	v_add_u32_e32 v156, s37, v142
	v_add_u32_e32 v174, s35, v142
	ds_read_b128 v[144:147], v156
	ds_read_b128 v[148:151], v156 offset:1024
	ds_read_b128 v[152:155], v156 offset:2048
	ds_read_b128 v[156:159], v156 offset:3072
	ds_read_b128 v[160:163], v174
	ds_read_b128 v[164:167], v174 offset:1024
	ds_read_b128 v[168:171], v174 offset:2048
	ds_read_b128 v[174:177], v174 offset:3072
	v_lshl_add_u64 v[212:213], s[14:15], 0, v[140:141]
	s_add_i32 m0, s23, 0xc000
	ds_read_b128 v[178:181], v143
	ds_read_b128 v[182:185], v143 offset:1024
	ds_read_b128 v[188:191], v143 offset:2048
	ds_read_b128 v[192:195], v143 offset:3072
	ds_read_b128 v[196:199], v143 offset:4096
	ds_read_b128 v[200:203], v143 offset:5120
	ds_read_b128 v[204:207], v143 offset:6144
	ds_read_b128 v[208:211], v143 offset:7168
	global_load_lds_dwordx4 v[212:213], off
	v_lshl_add_u64 v[212:213], s[14:15], 0, v[138:139]
	s_add_i32 m0, s23, 0xe000
	s_nop 0
	global_load_lds_dwordx4 v[212:213], off
	s_waitcnt vmcnt(8)
	s_waitcnt lgkmcnt(0)
	s_barrier
	s_waitcnt lgkmcnt(0)
	v_mfma_f32_16x16x32_bf16 v[128:131], v[144:147], v[178:181], v[128:131]
	v_mfma_f32_16x16x32_bf16 v[124:127], v[152:155], v[178:181], v[124:127]
	v_mfma_f32_16x16x32_bf16 v[112:115], v[144:147], v[188:191], v[112:115]
	v_mfma_f32_16x16x32_bf16 v[108:111], v[152:155], v[188:191], v[108:111]
	v_mfma_f32_16x16x32_bf16 v[96:99], v[144:147], v[196:199], v[96:99]
	v_mfma_f32_16x16x32_bf16 v[92:95], v[152:155], v[196:199], v[92:95]
	v_mfma_f32_16x16x32_bf16 v[78:81], v[144:147], v[204:207], v[78:81]
	v_mfma_f32_16x16x32_bf16 v[74:77], v[152:155], v[204:207], v[74:77]
	v_mfma_f32_16x16x32_bf16 v[128:131], v[148:151], v[182:185], v[128:131]
	v_mfma_f32_16x16x32_bf16 v[124:127], v[156:159], v[182:185], v[124:127]
	v_mfma_f32_16x16x32_bf16 v[112:115], v[148:151], v[192:195], v[112:115]
	v_mfma_f32_16x16x32_bf16 v[108:111], v[156:159], v[192:195], v[108:111]
	v_mfma_f32_16x16x32_bf16 v[96:99], v[148:151], v[200:203], v[96:99]
	v_mfma_f32_16x16x32_bf16 v[92:95], v[156:159], v[200:203], v[92:95]
	v_mfma_f32_16x16x32_bf16 v[78:81], v[148:151], v[208:211], v[78:81]
	v_mfma_f32_16x16x32_bf16 v[74:77], v[156:159], v[208:211], v[74:77]
	v_mfma_f32_16x16x32_bf16 v[120:123], v[160:163], v[178:181], v[120:123]
	v_mfma_f32_16x16x32_bf16 v[116:119], v[168:171], v[178:181], v[116:119]
	v_mfma_f32_16x16x32_bf16 v[104:107], v[160:163], v[188:191], v[104:107]
	v_mfma_f32_16x16x32_bf16 v[100:103], v[168:171], v[188:191], v[100:103]
	v_mfma_f32_16x16x32_bf16 v[88:91], v[160:163], v[196:199], v[88:91]
	v_mfma_f32_16x16x32_bf16 v[84:87], v[168:171], v[196:199], v[84:87]
	v_mfma_f32_16x16x32_bf16 v[70:73], v[160:163], v[204:207], v[70:73]
	v_mfma_f32_16x16x32_bf16 v[66:69], v[168:171], v[204:207], v[66:69]
	v_mfma_f32_16x16x32_bf16 v[120:123], v[164:167], v[182:185], v[120:123]
	v_mfma_f32_16x16x32_bf16 v[116:119], v[174:177], v[182:185], v[116:119]
	v_mfma_f32_16x16x32_bf16 v[104:107], v[164:167], v[192:195], v[104:107]
	v_mfma_f32_16x16x32_bf16 v[100:103], v[174:177], v[192:195], v[100:103]
	v_mfma_f32_16x16x32_bf16 v[88:91], v[164:167], v[200:203], v[88:91]
	v_mfma_f32_16x16x32_bf16 v[84:87], v[174:177], v[200:203], v[84:87]
	v_mfma_f32_16x16x32_bf16 v[70:73], v[164:167], v[208:211], v[70:73]
	v_mfma_f32_16x16x32_bf16 v[66:69], v[174:177], v[208:211], v[66:69]
	s_barrier
	s_add_i32 s36, s37, s22
	v_lshl_add_u64 v[212:213], s[16:17], 0, v[82:83]
	s_mov_b32 m0, s36
	ds_read_b128 v[178:181], v143 offset:16384
	ds_read_b128 v[182:185], v143 offset:17408
	ds_read_b128 v[188:191], v143 offset:18432
	ds_read_b128 v[192:195], v143 offset:19456
	ds_read_b128 v[196:199], v143 offset:20480
	ds_read_b128 v[200:203], v143 offset:21504
	ds_read_b128 v[204:207], v143 offset:22528
	ds_read_b128 v[208:211], v143 offset:23552
	global_load_lds_dwordx4 v[212:213], off
	s_add_i32 m0, s36, 0x2000
	s_add_u32 s36, s16, 0x80000
	v_lshl_add_u64 v[214:215], s[16:17], 0, v[136:137]
	s_addc_u32 s37, s17, 0
	s_add_i32 s35, s35, s22
	global_load_lds_dwordx4 v[214:215], off
	v_lshl_add_u64 v[216:217], s[36:37], 0, v[82:83]
	s_mov_b32 m0, s35
	v_lshl_add_u64 v[218:219], s[18:19], 0, v[134:135]
	global_load_lds_dwordx4 v[216:217], off
	v_lshl_add_u64 v[216:217], s[36:37], 0, v[136:137]
	s_add_i32 m0, s35, 0x2000
	s_nop 0
	global_load_lds_dwordx4 v[216:217], off
	v_lshl_add_u64 v[216:217], s[18:19], 0, v[132:133]
	s_mov_b32 m0, s23
	s_nop 0
	global_load_lds_dwordx4 v[216:217], off
	s_mov_b32 m0, s25
	s_nop 0
	global_load_lds_dwordx4 v[218:219], off
	s_waitcnt vmcnt(8)
	s_waitcnt lgkmcnt(0)
	s_barrier
	s_waitcnt lgkmcnt(0)
	v_mfma_f32_16x16x32_bf16 v[62:65], v[144:147], v[178:181], v[62:65]
	v_mfma_f32_16x16x32_bf16 v[58:61], v[152:155], v[178:181], v[58:61]
	v_mfma_f32_16x16x32_bf16 v[46:49], v[144:147], v[188:191], v[46:49]
	v_mfma_f32_16x16x32_bf16 v[42:45], v[152:155], v[188:191], v[42:45]
	v_mfma_f32_16x16x32_bf16 v[30:33], v[144:147], v[196:199], v[30:33]
	v_mfma_f32_16x16x32_bf16 v[26:29], v[152:155], v[196:199], v[26:29]
	v_mfma_f32_16x16x32_bf16 v[14:17], v[144:147], v[204:207], v[14:17]
	v_mfma_f32_16x16x32_bf16 v[10:13], v[152:155], v[204:207], v[10:13]
	v_mfma_f32_16x16x32_bf16 v[62:65], v[148:151], v[182:185], v[62:65]
	v_mfma_f32_16x16x32_bf16 v[58:61], v[156:159], v[182:185], v[58:61]
	v_mfma_f32_16x16x32_bf16 v[46:49], v[148:151], v[192:195], v[46:49]
	v_mfma_f32_16x16x32_bf16 v[42:45], v[156:159], v[192:195], v[42:45]
	v_mfma_f32_16x16x32_bf16 v[30:33], v[148:151], v[200:203], v[30:33]
	v_mfma_f32_16x16x32_bf16 v[26:29], v[156:159], v[200:203], v[26:29]
	v_mfma_f32_16x16x32_bf16 v[14:17], v[148:151], v[208:211], v[14:17]
	v_mfma_f32_16x16x32_bf16 v[10:13], v[156:159], v[208:211], v[10:13]
	v_mfma_f32_16x16x32_bf16 v[54:57], v[160:163], v[178:181], v[54:57]
	v_mfma_f32_16x16x32_bf16 v[50:53], v[168:171], v[178:181], v[50:53]
	v_mfma_f32_16x16x32_bf16 v[38:41], v[160:163], v[188:191], v[38:41]
	v_mfma_f32_16x16x32_bf16 v[34:37], v[168:171], v[188:191], v[34:37]
	v_mfma_f32_16x16x32_bf16 v[22:25], v[160:163], v[196:199], v[22:25]
	v_mfma_f32_16x16x32_bf16 v[18:21], v[168:171], v[196:199], v[18:21]
	v_mfma_f32_16x16x32_bf16 v[6:9], v[160:163], v[204:207], v[6:9]
	v_mfma_f32_16x16x32_bf16 v[2:5], v[168:171], v[204:207], v[2:5]
	v_mfma_f32_16x16x32_bf16 v[54:57], v[164:167], v[182:185], v[54:57]
	v_mfma_f32_16x16x32_bf16 v[50:53], v[174:177], v[182:185], v[50:53]
	v_mfma_f32_16x16x32_bf16 v[38:41], v[164:167], v[192:195], v[38:41]
	v_mfma_f32_16x16x32_bf16 v[34:37], v[174:177], v[192:195], v[34:37]
	v_mfma_f32_16x16x32_bf16 v[22:25], v[164:167], v[200:203], v[22:25]
	v_mfma_f32_16x16x32_bf16 v[18:21], v[174:177], v[200:203], v[18:21]
	v_mfma_f32_16x16x32_bf16 v[6:9], v[164:167], v[208:211], v[6:9]
	v_mfma_f32_16x16x32_bf16 v[2:5], v[174:177], v[208:211], v[2:5]
	s_barrier
	s_add_i32 s35, 0, 0x18000
	s_add_i32 s36, 0, 0x1c000
	v_add_u32_e32 v156, s35, v142
	v_add_u32_e32 v174, s36, v142
	ds_read_b128 v[144:147], v156
	ds_read_b128 v[148:151], v156 offset:1024
	ds_read_b128 v[152:155], v156 offset:2048
	ds_read_b128 v[156:159], v156 offset:3072
	ds_read_b128 v[160:163], v174
	ds_read_b128 v[164:167], v174 offset:1024
	ds_read_b128 v[168:171], v174 offset:2048
	ds_read_b128 v[174:177], v174 offset:3072
	s_add_u32 s18, s18, 0x80000
	s_addc_u32 s19, s19, 0
	s_mov_b32 m0, s26
	v_lshl_add_u64 v[220:221], s[18:19], 0, v[132:133]
	ds_read_b128 v[178:181], v143 offset:32768
	ds_read_b128 v[182:185], v143 offset:33792
	ds_read_b128 v[188:191], v143 offset:34816
	ds_read_b128 v[192:195], v143 offset:35840
	ds_read_b128 v[196:199], v143 offset:36864
	ds_read_b128 v[200:203], v143 offset:37888
	ds_read_b128 v[204:207], v143 offset:38912
	ds_read_b128 v[208:211], v143 offset:39936
	global_load_lds_dwordx4 v[220:221], off
	v_lshl_add_u64 v[220:221], s[18:19], 0, v[134:135]
	s_mov_b32 m0, s27
	s_nop 0
	global_load_lds_dwordx4 v[220:221], off
	s_waitcnt vmcnt(8)
	s_waitcnt lgkmcnt(0)
	s_barrier
	s_waitcnt lgkmcnt(0)
	v_mfma_f32_16x16x32_bf16 v[128:131], v[144:147], v[178:181], v[128:131]
	v_mfma_f32_16x16x32_bf16 v[124:127], v[152:155], v[178:181], v[124:127]
	v_mfma_f32_16x16x32_bf16 v[112:115], v[144:147], v[188:191], v[112:115]
	v_mfma_f32_16x16x32_bf16 v[108:111], v[152:155], v[188:191], v[108:111]
	v_mfma_f32_16x16x32_bf16 v[96:99], v[144:147], v[196:199], v[96:99]
	v_mfma_f32_16x16x32_bf16 v[92:95], v[152:155], v[196:199], v[92:95]
	v_mfma_f32_16x16x32_bf16 v[78:81], v[144:147], v[204:207], v[78:81]
	v_mfma_f32_16x16x32_bf16 v[74:77], v[152:155], v[204:207], v[74:77]
	v_mfma_f32_16x16x32_bf16 v[128:131], v[148:151], v[182:185], v[128:131]
	v_mfma_f32_16x16x32_bf16 v[124:127], v[156:159], v[182:185], v[124:127]
	v_mfma_f32_16x16x32_bf16 v[112:115], v[148:151], v[192:195], v[112:115]
	v_mfma_f32_16x16x32_bf16 v[108:111], v[156:159], v[192:195], v[108:111]
	v_mfma_f32_16x16x32_bf16 v[96:99], v[148:151], v[200:203], v[96:99]
	v_mfma_f32_16x16x32_bf16 v[92:95], v[156:159], v[200:203], v[92:95]
	v_mfma_f32_16x16x32_bf16 v[78:81], v[148:151], v[208:211], v[78:81]
	v_mfma_f32_16x16x32_bf16 v[74:77], v[156:159], v[208:211], v[74:77]
	v_mfma_f32_16x16x32_bf16 v[120:123], v[160:163], v[178:181], v[120:123]
	v_mfma_f32_16x16x32_bf16 v[116:119], v[168:171], v[178:181], v[116:119]
	v_mfma_f32_16x16x32_bf16 v[104:107], v[160:163], v[188:191], v[104:107]
	v_mfma_f32_16x16x32_bf16 v[100:103], v[168:171], v[188:191], v[100:103]
	v_mfma_f32_16x16x32_bf16 v[88:91], v[160:163], v[196:199], v[88:91]
	v_mfma_f32_16x16x32_bf16 v[84:87], v[168:171], v[196:199], v[84:87]
	v_mfma_f32_16x16x32_bf16 v[70:73], v[160:163], v[204:207], v[70:73]
	v_mfma_f32_16x16x32_bf16 v[66:69], v[168:171], v[204:207], v[66:69]
	v_mfma_f32_16x16x32_bf16 v[120:123], v[164:167], v[182:185], v[120:123]
	v_mfma_f32_16x16x32_bf16 v[116:119], v[174:177], v[182:185], v[116:119]
	v_mfma_f32_16x16x32_bf16 v[104:107], v[164:167], v[192:195], v[104:107]
	v_mfma_f32_16x16x32_bf16 v[100:103], v[174:177], v[192:195], v[100:103]
	v_mfma_f32_16x16x32_bf16 v[88:91], v[164:167], v[200:203], v[88:91]
	v_mfma_f32_16x16x32_bf16 v[84:87], v[174:177], v[200:203], v[84:87]
	v_mfma_f32_16x16x32_bf16 v[70:73], v[164:167], v[208:211], v[70:73]
	v_mfma_f32_16x16x32_bf16 v[66:69], v[174:177], v[208:211], v[66:69]
	s_barrier
	s_add_i32 s18, s35, s22
	v_lshl_add_u64 v[212:213], v[212:213], 0, s[68:69]
	s_mov_b32 m0, s18
	ds_read_b128 v[178:181], v143 offset:49152
	ds_read_b128 v[182:185], v143 offset:50176
	ds_read_b128 v[188:191], v143 offset:51200
	ds_read_b128 v[192:195], v143 offset:52224
	ds_read_b128 v[196:199], v143 offset:53248
	ds_read_b128 v[200:203], v143 offset:54272
	ds_read_b128 v[204:207], v143 offset:55296
	ds_read_b128 v[208:211], v143 offset:56320
	global_load_lds_dwordx4 v[212:213], off
	s_add_i32 m0, s18, 0x2000
	s_add_u32 s16, s16, 0x80080
	v_lshl_add_u64 v[212:213], v[214:215], 0, s[68:69]
	s_addc_u32 s17, s17, 0
	s_add_i32 s18, s36, s22
	global_load_lds_dwordx4 v[212:213], off
	v_lshl_add_u64 v[212:213], s[16:17], 0, v[82:83]
	s_mov_b32 m0, s18
	s_nop 0
	global_load_lds_dwordx4 v[212:213], off
	v_lshl_add_u64 v[212:213], s[16:17], 0, v[136:137]
	s_add_i32 m0, s18, 0x2000
	s_nop 0
	global_load_lds_dwordx4 v[212:213], off
	v_lshl_add_u64 v[212:213], v[216:217], 0, s[68:69]
	s_mov_b32 m0, s28
	s_nop 0
	global_load_lds_dwordx4 v[212:213], off
	v_lshl_add_u64 v[212:213], v[218:219], 0, s[68:69]
	s_mov_b32 m0, s29
	s_nop 0
	global_load_lds_dwordx4 v[212:213], off
	s_waitcnt vmcnt(8)
	s_waitcnt lgkmcnt(0)
	s_barrier
	s_waitcnt lgkmcnt(0)
	v_mfma_f32_16x16x32_bf16 v[62:65], v[144:147], v[178:181], v[62:65]
	v_mfma_f32_16x16x32_bf16 v[58:61], v[152:155], v[178:181], v[58:61]
	v_mfma_f32_16x16x32_bf16 v[46:49], v[144:147], v[188:191], v[46:49]
	v_mfma_f32_16x16x32_bf16 v[42:45], v[152:155], v[188:191], v[42:45]
	v_mfma_f32_16x16x32_bf16 v[30:33], v[144:147], v[196:199], v[30:33]
	v_mfma_f32_16x16x32_bf16 v[26:29], v[152:155], v[196:199], v[26:29]
	v_mfma_f32_16x16x32_bf16 v[14:17], v[144:147], v[204:207], v[14:17]
	v_mfma_f32_16x16x32_bf16 v[10:13], v[152:155], v[204:207], v[10:13]
	v_mfma_f32_16x16x32_bf16 v[62:65], v[148:151], v[182:185], v[62:65]
	v_mfma_f32_16x16x32_bf16 v[58:61], v[156:159], v[182:185], v[58:61]
	v_mfma_f32_16x16x32_bf16 v[46:49], v[148:151], v[192:195], v[46:49]
	v_mfma_f32_16x16x32_bf16 v[42:45], v[156:159], v[192:195], v[42:45]
	v_mfma_f32_16x16x32_bf16 v[30:33], v[148:151], v[200:203], v[30:33]
	v_mfma_f32_16x16x32_bf16 v[26:29], v[156:159], v[200:203], v[26:29]
	v_mfma_f32_16x16x32_bf16 v[14:17], v[148:151], v[208:211], v[14:17]
	v_mfma_f32_16x16x32_bf16 v[10:13], v[156:159], v[208:211], v[10:13]
	v_mfma_f32_16x16x32_bf16 v[54:57], v[160:163], v[178:181], v[54:57]
	v_mfma_f32_16x16x32_bf16 v[50:53], v[168:171], v[178:181], v[50:53]
	v_mfma_f32_16x16x32_bf16 v[38:41], v[160:163], v[188:191], v[38:41]
	v_mfma_f32_16x16x32_bf16 v[34:37], v[168:171], v[188:191], v[34:37]
	v_mfma_f32_16x16x32_bf16 v[22:25], v[160:163], v[196:199], v[22:25]
	v_mfma_f32_16x16x32_bf16 v[18:21], v[168:171], v[196:199], v[18:21]
	v_mfma_f32_16x16x32_bf16 v[6:9], v[160:163], v[204:207], v[6:9]
	v_mfma_f32_16x16x32_bf16 v[2:5], v[168:171], v[204:207], v[2:5]
	v_mfma_f32_16x16x32_bf16 v[54:57], v[164:167], v[182:185], v[54:57]
	v_mfma_f32_16x16x32_bf16 v[50:53], v[174:177], v[182:185], v[50:53]
	v_mfma_f32_16x16x32_bf16 v[38:41], v[164:167], v[192:195], v[38:41]
	v_mfma_f32_16x16x32_bf16 v[34:37], v[174:177], v[192:195], v[34:37]
	v_mfma_f32_16x16x32_bf16 v[22:25], v[164:167], v[200:203], v[22:25]
	v_mfma_f32_16x16x32_bf16 v[18:21], v[174:177], v[200:203], v[18:21]
	v_mfma_f32_16x16x32_bf16 v[6:9], v[164:167], v[208:211], v[6:9]
	v_mfma_f32_16x16x32_bf16 v[2:5], v[174:177], v[208:211], v[2:5]
	s_barrier
	s_add_i32 s34, s34, 2
	s_add_u32 s14, s14, 0x100
	s_addc_u32 s15, s15, 0
	s_cmp_gt_u32 s34, 29
	s_cbranch_scc0 .LBB0_389
	s_cmpk_lt_u32 s21, 0x100
	s_cbranch_scc0 .LBB0_392
	s_barrier

.LBB0_1127:
	s_add_i32 s29, s27, 2
	s_add_u32 s39, s40, 0xfff80080
	s_addc_u32 s54, s41, -1
	s_add_i32 s90, 0, 0x10000
	s_cmp_eq_u32 s85, s27
	s_cselect_b32 s59, s31, s54
	s_cselect_b32 s58, s30, s39
	s_cselect_b32 s55, s35, s25
	s_cselect_b32 s54, s34, s19
	s_add_i32 s27, 0, 0x14000
	v_add_u32_e32 v144, s90, v201
	v_add_u32_e32 v160, s27, v201
	ds_read_b128 v[132:135], v144
	ds_read_b128 v[136:139], v144 offset:1024
	ds_read_b128 v[140:143], v144 offset:2048
	ds_read_b128 v[144:147], v144 offset:3072
	ds_read_b128 v[148:151], v160
	ds_read_b128 v[152:155], v160 offset:1024
	ds_read_b128 v[156:159], v160 offset:2048
	ds_read_b128 v[160:163], v160 offset:3072
	v_lshl_add_u64 v[198:199], s[40:41], 0, v[172:173]
	s_add_i32 m0, s74, 0xc000
	ds_read_b128 v[174:177], v202
	ds_read_b128 v[178:181], v202 offset:1024
	ds_read_b128 v[182:185], v202 offset:2048
	ds_read_b128 v[186:189], v202 offset:3072
	ds_read_b128 v[190:193], v202 offset:4096
	ds_read_b128 v[194:197], v202 offset:5120
	ds_read_b128 v[204:207], v202 offset:6144
	ds_read_b128 v[208:211], v202 offset:7168
	global_load_lds_dwordx4 v[198:199], off
	v_lshl_add_u64 v[198:199], s[40:41], 0, v[170:171]
	s_add_i32 m0, s74, 0xe000
	s_nop 0
	global_load_lds_dwordx4 v[198:199], off
	s_waitcnt vmcnt(8)
	s_waitcnt lgkmcnt(0)
	s_barrier
	s_waitcnt lgkmcnt(0)
	v_mfma_f32_16x16x32_bf16 v[128:131], v[132:135], v[174:177], v[128:131]
	v_mfma_f32_16x16x32_bf16 v[124:127], v[140:143], v[174:177], v[124:127]
	v_mfma_f32_16x16x32_bf16 v[120:123], v[132:135], v[182:185], v[120:123]
	v_mfma_f32_16x16x32_bf16 v[116:119], v[140:143], v[182:185], v[116:119]
	v_mfma_f32_16x16x32_bf16 v[108:111], v[132:135], v[190:193], v[108:111]
	v_mfma_f32_16x16x32_bf16 v[100:103], v[140:143], v[190:193], v[100:103]
	v_mfma_f32_16x16x32_bf16 v[92:95], v[132:135], v[204:207], v[92:95]
	v_mfma_f32_16x16x32_bf16 v[84:87], v[140:143], v[204:207], v[84:87]
	v_mfma_f32_16x16x32_bf16 v[128:131], v[136:139], v[178:181], v[128:131]
	v_mfma_f32_16x16x32_bf16 v[124:127], v[144:147], v[178:181], v[124:127]
	v_mfma_f32_16x16x32_bf16 v[120:123], v[136:139], v[186:189], v[120:123]
	v_mfma_f32_16x16x32_bf16 v[116:119], v[144:147], v[186:189], v[116:119]
	v_mfma_f32_16x16x32_bf16 v[108:111], v[136:139], v[194:197], v[108:111]
	v_mfma_f32_16x16x32_bf16 v[100:103], v[144:147], v[194:197], v[100:103]
	v_mfma_f32_16x16x32_bf16 v[92:95], v[136:139], v[208:211], v[92:95]
	v_mfma_f32_16x16x32_bf16 v[84:87], v[144:147], v[208:211], v[84:87]
	v_mfma_f32_16x16x32_bf16 v[112:115], v[148:151], v[174:177], v[112:115]
	v_mfma_f32_16x16x32_bf16 v[104:107], v[156:159], v[174:177], v[104:107]
	v_mfma_f32_16x16x32_bf16 v[96:99], v[148:151], v[182:185], v[96:99]
	v_mfma_f32_16x16x32_bf16 v[88:91], v[156:159], v[182:185], v[88:91]
	v_mfma_f32_16x16x32_bf16 v[78:81], v[148:151], v[190:193], v[78:81]
	v_mfma_f32_16x16x32_bf16 v[74:77], v[156:159], v[190:193], v[74:77]
	v_mfma_f32_16x16x32_bf16 v[70:73], v[148:151], v[204:207], v[70:73]
	v_mfma_f32_16x16x32_bf16 v[66:69], v[156:159], v[204:207], v[66:69]
	v_mfma_f32_16x16x32_bf16 v[112:115], v[152:155], v[178:181], v[112:115]
	v_mfma_f32_16x16x32_bf16 v[104:107], v[160:163], v[178:181], v[104:107]
	v_mfma_f32_16x16x32_bf16 v[96:99], v[152:155], v[186:189], v[96:99]
	v_mfma_f32_16x16x32_bf16 v[88:91], v[160:163], v[186:189], v[88:91]
	v_mfma_f32_16x16x32_bf16 v[78:81], v[152:155], v[194:197], v[78:81]
	v_mfma_f32_16x16x32_bf16 v[74:77], v[160:163], v[194:197], v[74:77]
	v_mfma_f32_16x16x32_bf16 v[70:73], v[152:155], v[208:211], v[70:73]
	v_mfma_f32_16x16x32_bf16 v[66:69], v[160:163], v[208:211], v[66:69]
	s_barrier
	s_add_i32 s39, s90, s72
	v_lshl_add_u64 v[198:199], s[54:55], 0, v[82:83]
	s_mov_b32 m0, s39
	ds_read_b128 v[174:177], v202 offset:16384
	ds_read_b128 v[178:181], v202 offset:17408
	ds_read_b128 v[182:185], v202 offset:18432
	ds_read_b128 v[186:189], v202 offset:19456
	ds_read_b128 v[190:193], v202 offset:20480
	ds_read_b128 v[194:197], v202 offset:21504
	ds_read_b128 v[204:207], v202 offset:22528
	ds_read_b128 v[208:211], v202 offset:23552
	global_load_lds_dwordx4 v[198:199], off
	s_add_i32 m0, s39, 0x2000
	s_add_u32 s90, s54, 0x80000
	v_lshl_add_u64 v[212:213], s[54:55], 0, v[168:169]
	s_addc_u32 s91, s55, 0
	s_add_i32 s27, s27, s72
	global_load_lds_dwordx4 v[212:213], off
	v_lshl_add_u64 v[214:215], s[90:91], 0, v[82:83]
	s_mov_b32 m0, s27
	v_lshl_add_u64 v[216:217], s[58:59], 0, v[166:167]
	global_load_lds_dwordx4 v[214:215], off
	v_lshl_add_u64 v[214:215], s[90:91], 0, v[168:169]
	s_add_i32 m0, s27, 0x2000
	s_nop 0
	global_load_lds_dwordx4 v[214:215], off
	v_lshl_add_u64 v[214:215], s[58:59], 0, v[164:165]
	s_mov_b32 m0, s74
	s_nop 0
	global_load_lds_dwordx4 v[214:215], off
	s_mov_b32 m0, s75
	s_nop 0
	global_load_lds_dwordx4 v[216:217], off
	s_waitcnt vmcnt(8)
	s_waitcnt lgkmcnt(0)
	s_barrier
	s_waitcnt lgkmcnt(0)
	v_mfma_f32_16x16x32_bf16 v[62:65], v[132:135], v[174:177], v[62:65]
	v_mfma_f32_16x16x32_bf16 v[58:61], v[140:143], v[174:177], v[58:61]
	v_mfma_f32_16x16x32_bf16 v[54:57], v[132:135], v[182:185], v[54:57]
	v_mfma_f32_16x16x32_bf16 v[50:53], v[140:143], v[182:185], v[50:53]
	v_mfma_f32_16x16x32_bf16 v[38:41], v[132:135], v[190:193], v[38:41]
	v_mfma_f32_16x16x32_bf16 v[34:37], v[140:143], v[190:193], v[34:37]
	v_mfma_f32_16x16x32_bf16 v[22:25], v[132:135], v[204:207], v[22:25]
	v_mfma_f32_16x16x32_bf16 v[18:21], v[140:143], v[204:207], v[18:21]
	v_mfma_f32_16x16x32_bf16 v[62:65], v[136:139], v[178:181], v[62:65]
	v_mfma_f32_16x16x32_bf16 v[58:61], v[144:147], v[178:181], v[58:61]
	v_mfma_f32_16x16x32_bf16 v[54:57], v[136:139], v[186:189], v[54:57]
	v_mfma_f32_16x16x32_bf16 v[50:53], v[144:147], v[186:189], v[50:53]
	v_mfma_f32_16x16x32_bf16 v[38:41], v[136:139], v[194:197], v[38:41]
	v_mfma_f32_16x16x32_bf16 v[34:37], v[144:147], v[194:197], v[34:37]
	v_mfma_f32_16x16x32_bf16 v[22:25], v[136:139], v[208:211], v[22:25]
	v_mfma_f32_16x16x32_bf16 v[18:21], v[144:147], v[208:211], v[18:21]
	v_mfma_f32_16x16x32_bf16 v[46:49], v[148:151], v[174:177], v[46:49]
	v_mfma_f32_16x16x32_bf16 v[42:45], v[156:159], v[174:177], v[42:45]
	v_mfma_f32_16x16x32_bf16 v[30:33], v[148:151], v[182:185], v[30:33]
	v_mfma_f32_16x16x32_bf16 v[26:29], v[156:159], v[182:185], v[26:29]
	v_mfma_f32_16x16x32_bf16 v[14:17], v[148:151], v[190:193], v[14:17]
	v_mfma_f32_16x16x32_bf16 v[10:13], v[156:159], v[190:193], v[10:13]
	v_mfma_f32_16x16x32_bf16 v[6:9], v[148:151], v[204:207], v[6:9]
	v_mfma_f32_16x16x32_bf16 v[2:5], v[156:159], v[204:207], v[2:5]
	v_mfma_f32_16x16x32_bf16 v[46:49], v[152:155], v[178:181], v[46:49]
	v_mfma_f32_16x16x32_bf16 v[42:45], v[160:163], v[178:181], v[42:45]
	v_mfma_f32_16x16x32_bf16 v[30:33], v[152:155], v[186:189], v[30:33]
	v_mfma_f32_16x16x32_bf16 v[26:29], v[160:163], v[186:189], v[26:29]
	v_mfma_f32_16x16x32_bf16 v[14:17], v[152:155], v[194:197], v[14:17]
	v_mfma_f32_16x16x32_bf16 v[10:13], v[160:163], v[194:197], v[10:13]
	v_mfma_f32_16x16x32_bf16 v[6:9], v[152:155], v[208:211], v[6:9]
	v_mfma_f32_16x16x32_bf16 v[2:5], v[160:163], v[208:211], v[2:5]
	s_barrier
	s_add_i32 s27, 0, 0x18000
	s_add_i32 s39, 0, 0x1c000
	v_add_u32_e32 v144, s27, v201
	v_add_u32_e32 v160, s39, v201
	ds_read_b128 v[132:135], v144
	ds_read_b128 v[136:139], v144 offset:1024
	ds_read_b128 v[140:143], v144 offset:2048
	ds_read_b128 v[144:147], v144 offset:3072
	ds_read_b128 v[148:151], v160
	ds_read_b128 v[152:155], v160 offset:1024
	ds_read_b128 v[156:159], v160 offset:2048
	ds_read_b128 v[160:163], v160 offset:3072
	s_add_u32 s58, s58, 0x80000
	s_addc_u32 s59, s59, 0
	s_mov_b32 m0, s76
	v_lshl_add_u64 v[218:219], s[58:59], 0, v[164:165]
	ds_read_b128 v[174:177], v202 offset:32768
	ds_read_b128 v[178:181], v202 offset:33792
	ds_read_b128 v[182:185], v202 offset:34816
	ds_read_b128 v[186:189], v202 offset:35840
	ds_read_b128 v[190:193], v202 offset:36864
	ds_read_b128 v[194:197], v202 offset:37888
	ds_read_b128 v[204:207], v202 offset:38912
	ds_read_b128 v[208:211], v202 offset:39936
	global_load_lds_dwordx4 v[218:219], off
	v_lshl_add_u64 v[218:219], s[58:59], 0, v[166:167]
	s_mov_b32 m0, s77
	s_nop 0
	global_load_lds_dwordx4 v[218:219], off
	s_waitcnt vmcnt(8)
	s_waitcnt lgkmcnt(0)
	s_barrier
	s_waitcnt lgkmcnt(0)
	v_mfma_f32_16x16x32_bf16 v[128:131], v[132:135], v[174:177], v[128:131]
	v_mfma_f32_16x16x32_bf16 v[124:127], v[140:143], v[174:177], v[124:127]
	v_mfma_f32_16x16x32_bf16 v[120:123], v[132:135], v[182:185], v[120:123]
	v_mfma_f32_16x16x32_bf16 v[116:119], v[140:143], v[182:185], v[116:119]
	v_mfma_f32_16x16x32_bf16 v[108:111], v[132:135], v[190:193], v[108:111]
	v_mfma_f32_16x16x32_bf16 v[100:103], v[140:143], v[190:193], v[100:103]
	v_mfma_f32_16x16x32_bf16 v[92:95], v[132:135], v[204:207], v[92:95]
	v_mfma_f32_16x16x32_bf16 v[84:87], v[140:143], v[204:207], v[84:87]
	v_mfma_f32_16x16x32_bf16 v[128:131], v[136:139], v[178:181], v[128:131]
	v_mfma_f32_16x16x32_bf16 v[124:127], v[144:147], v[178:181], v[124:127]
	v_mfma_f32_16x16x32_bf16 v[120:123], v[136:139], v[186:189], v[120:123]
	v_mfma_f32_16x16x32_bf16 v[116:119], v[144:147], v[186:189], v[116:119]
	v_mfma_f32_16x16x32_bf16 v[108:111], v[136:139], v[194:197], v[108:111]
	v_mfma_f32_16x16x32_bf16 v[100:103], v[144:147], v[194:197], v[100:103]
	v_mfma_f32_16x16x32_bf16 v[92:95], v[136:139], v[208:211], v[92:95]
	v_mfma_f32_16x16x32_bf16 v[84:87], v[144:147], v[208:211], v[84:87]
	v_mfma_f32_16x16x32_bf16 v[112:115], v[148:151], v[174:177], v[112:115]
	v_mfma_f32_16x16x32_bf16 v[104:107], v[156:159], v[174:177], v[104:107]
	v_mfma_f32_16x16x32_bf16 v[96:99], v[148:151], v[182:185], v[96:99]
	v_mfma_f32_16x16x32_bf16 v[88:91], v[156:159], v[182:185], v[88:91]
	v_mfma_f32_16x16x32_bf16 v[78:81], v[148:151], v[190:193], v[78:81]
	v_mfma_f32_16x16x32_bf16 v[74:77], v[156:159], v[190:193], v[74:77]
	v_mfma_f32_16x16x32_bf16 v[70:73], v[148:151], v[204:207], v[70:73]
	v_mfma_f32_16x16x32_bf16 v[66:69], v[156:159], v[204:207], v[66:69]
	v_mfma_f32_16x16x32_bf16 v[112:115], v[152:155], v[178:181], v[112:115]
	v_mfma_f32_16x16x32_bf16 v[104:107], v[160:163], v[178:181], v[104:107]
	v_mfma_f32_16x16x32_bf16 v[96:99], v[152:155], v[186:189], v[96:99]
	v_mfma_f32_16x16x32_bf16 v[88:91], v[160:163], v[186:189], v[88:91]
	v_mfma_f32_16x16x32_bf16 v[78:81], v[152:155], v[194:197], v[78:81]
	v_mfma_f32_16x16x32_bf16 v[74:77], v[160:163], v[194:197], v[74:77]
	v_mfma_f32_16x16x32_bf16 v[70:73], v[152:155], v[208:211], v[70:73]
	v_mfma_f32_16x16x32_bf16 v[66:69], v[160:163], v[208:211], v[66:69]
	s_barrier
	s_add_i32 s27, s27, s72
	v_lshl_add_u64 v[198:199], v[198:199], 0, s[68:69]
	s_mov_b32 m0, s27
	ds_read_b128 v[174:177], v202 offset:49152
	ds_read_b128 v[178:181], v202 offset:50176
	ds_read_b128 v[182:185], v202 offset:51200
	ds_read_b128 v[186:189], v202 offset:52224
	ds_read_b128 v[190:193], v202 offset:53248
	ds_read_b128 v[194:197], v202 offset:54272
	ds_read_b128 v[204:207], v202 offset:55296
	ds_read_b128 v[208:211], v202 offset:56320
	global_load_lds_dwordx4 v[198:199], off
	s_add_i32 m0, s27, 0x2000
	s_add_u32 s54, s54, 0x80080
	v_lshl_add_u64 v[198:199], v[212:213], 0, s[68:69]
	s_addc_u32 s55, s55, 0
	s_add_i32 s27, s39, s72
	global_load_lds_dwordx4 v[198:199], off
	v_lshl_add_u64 v[198:199], s[54:55], 0, v[82:83]
	s_mov_b32 m0, s27
	s_nop 0
	global_load_lds_dwordx4 v[198:199], off
	v_lshl_add_u64 v[198:199], s[54:55], 0, v[168:169]
	s_add_i32 m0, s27, 0x2000
	s_nop 0
	global_load_lds_dwordx4 v[198:199], off
	v_lshl_add_u64 v[198:199], v[214:215], 0, s[68:69]
	s_mov_b32 m0, s81
	s_nop 0
	global_load_lds_dwordx4 v[198:199], off
	v_lshl_add_u64 v[198:199], v[216:217], 0, s[68:69]
	s_mov_b32 m0, s84
	s_nop 0
	global_load_lds_dwordx4 v[198:199], off
	s_waitcnt vmcnt(8)
	s_waitcnt lgkmcnt(0)
	s_barrier
	s_waitcnt lgkmcnt(0)
	v_mfma_f32_16x16x32_bf16 v[62:65], v[132:135], v[174:177], v[62:65]
	v_mfma_f32_16x16x32_bf16 v[58:61], v[140:143], v[174:177], v[58:61]
	v_mfma_f32_16x16x32_bf16 v[54:57], v[132:135], v[182:185], v[54:57]
	v_mfma_f32_16x16x32_bf16 v[50:53], v[140:143], v[182:185], v[50:53]
	v_mfma_f32_16x16x32_bf16 v[38:41], v[132:135], v[190:193], v[38:41]
	v_mfma_f32_16x16x32_bf16 v[34:37], v[140:143], v[190:193], v[34:37]
	v_mfma_f32_16x16x32_bf16 v[22:25], v[132:135], v[204:207], v[22:25]
	v_mfma_f32_16x16x32_bf16 v[18:21], v[140:143], v[204:207], v[18:21]
	v_mfma_f32_16x16x32_bf16 v[62:65], v[136:139], v[178:181], v[62:65]
	v_mfma_f32_16x16x32_bf16 v[58:61], v[144:147], v[178:181], v[58:61]
	v_mfma_f32_16x16x32_bf16 v[54:57], v[136:139], v[186:189], v[54:57]
	v_mfma_f32_16x16x32_bf16 v[50:53], v[144:147], v[186:189], v[50:53]
	v_mfma_f32_16x16x32_bf16 v[38:41], v[136:139], v[194:197], v[38:41]
	v_mfma_f32_16x16x32_bf16 v[34:37], v[144:147], v[194:197], v[34:37]
	v_mfma_f32_16x16x32_bf16 v[22:25], v[136:139], v[208:211], v[22:25]
	v_mfma_f32_16x16x32_bf16 v[18:21], v[144:147], v[208:211], v[18:21]
	v_mfma_f32_16x16x32_bf16 v[46:49], v[148:151], v[174:177], v[46:49]
	v_mfma_f32_16x16x32_bf16 v[42:45], v[156:159], v[174:177], v[42:45]
	v_mfma_f32_16x16x32_bf16 v[30:33], v[148:151], v[182:185], v[30:33]
	v_mfma_f32_16x16x32_bf16 v[26:29], v[156:159], v[182:185], v[26:29]
	v_mfma_f32_16x16x32_bf16 v[14:17], v[148:151], v[190:193], v[14:17]
	v_mfma_f32_16x16x32_bf16 v[10:13], v[156:159], v[190:193], v[10:13]
	v_mfma_f32_16x16x32_bf16 v[6:9], v[148:151], v[204:207], v[6:9]
	v_mfma_f32_16x16x32_bf16 v[2:5], v[156:159], v[204:207], v[2:5]
	v_mfma_f32_16x16x32_bf16 v[46:49], v[152:155], v[178:181], v[46:49]
	v_mfma_f32_16x16x32_bf16 v[42:45], v[160:163], v[178:181], v[42:45]
	v_mfma_f32_16x16x32_bf16 v[30:33], v[152:155], v[186:189], v[30:33]
	v_mfma_f32_16x16x32_bf16 v[26:29], v[160:163], v[186:189], v[26:29]
	v_mfma_f32_16x16x32_bf16 v[14:17], v[152:155], v[194:197], v[14:17]
	v_mfma_f32_16x16x32_bf16 v[10:13], v[160:163], v[194:197], v[10:13]
	v_mfma_f32_16x16x32_bf16 v[6:9], v[152:155], v[208:211], v[6:9]
	v_mfma_f32_16x16x32_bf16 v[2:5], v[160:163], v[208:211], v[2:5]
	s_barrier
	s_add_u32 s19, s19, 0x100
	s_addc_u32 s25, s25, 0
	s_add_u32 s40, s40, 0x100
	s_addc_u32 s41, s41, 0
	s_cmp_ge_u32 s29, s78
	s_mov_b32 s27, s29
	s_cbranch_scc0 .LBB0_1127
	s_and_b64 vcc, exec, s[22:23]
	s_cbranch_vccz .LBB0_1130
	s_barrier

.LBB0_1290:
	s_mov_b32 s12, 0xfff80080
	s_add_i32 s20, 0, 0x10000
	s_mov_b32 s13, -1
	s_cmp_eq_u32 s19, 28
	v_lshl_add_u64 v[4:5], v[2:3], 0, s[12:13]
	s_cselect_b64 vcc, -1, 0
	v_add_u32_e32 v8, s20, v225
	s_cselect_b32 s13, s15, s17
	s_cselect_b32 s12, s18, s16
	s_add_i32 s23, 0, 0x14000
	v_cndmask_b32_e32 v223, v5, v221, vcc
	v_cndmask_b32_e32 v222, v4, v220, vcc
	ds_read_b128 v[4:7], v8
	ds_read_b128 v[50:53], v8 offset:1024
	ds_read_b128 v[58:61], v8 offset:2048
	ds_read_b128 v[62:65], v8 offset:3072
	v_add_u32_e32 v8, s23, v225
	ds_read_b128 v[66:69], v8
	ds_read_b128 v[74:77], v8 offset:1024
	ds_read_b128 v[78:81], v8 offset:2048
	ds_read_b128 v[84:87], v8 offset:3072
	v_lshl_add_u64 v[8:9], v[2:3], 0, v[218:219]
	s_add_i32 m0, s91, 0xc000
	ds_read_b128 v[88:91], v233
	ds_read_b128 v[92:95], v233 offset:1024
	ds_read_b128 v[178:181], v233 offset:2048
	ds_read_b128 v[182:185], v233 offset:3072
	ds_read_b128 v[186:189], v233 offset:4096
	ds_read_b128 v[190:193], v233 offset:5120
	ds_read_b128 v[194:197], v233 offset:6144
	ds_read_b128 v[198:201], v233 offset:7168
	global_load_lds_dwordx4 v[8:9], off
	v_lshl_add_u64 v[8:9], v[2:3], 0, v[216:217]
	s_add_i32 m0, s91, 0xe000
	s_nop 0
	global_load_lds_dwordx4 v[8:9], off
	s_waitcnt vmcnt(8)
	s_waitcnt lgkmcnt(0)
	s_barrier
	s_waitcnt lgkmcnt(0)
	v_mfma_f32_16x16x32_bf16 v[170:173], v[4:7], v[88:91], v[170:173]
	v_mfma_f32_16x16x32_bf16 v[174:177], v[58:61], v[88:91], v[174:177]
	v_mfma_f32_16x16x32_bf16 v[154:157], v[4:7], v[178:181], v[154:157]
	v_mfma_f32_16x16x32_bf16 v[158:161], v[58:61], v[178:181], v[158:161]
	v_mfma_f32_16x16x32_bf16 v[138:141], v[4:7], v[186:189], v[138:141]
	v_mfma_f32_16x16x32_bf16 v[142:145], v[58:61], v[186:189], v[142:145]
	v_mfma_f32_16x16x32_bf16 v[122:125], v[4:7], v[194:197], v[122:125]
	v_mfma_f32_16x16x32_bf16 v[126:129], v[58:61], v[194:197], v[126:129]
	v_mfma_f32_16x16x32_bf16 v[170:173], v[50:53], v[92:95], v[170:173]
	v_mfma_f32_16x16x32_bf16 v[174:177], v[62:65], v[92:95], v[174:177]
	v_mfma_f32_16x16x32_bf16 v[154:157], v[50:53], v[182:185], v[154:157]
	v_mfma_f32_16x16x32_bf16 v[158:161], v[62:65], v[182:185], v[158:161]
	v_mfma_f32_16x16x32_bf16 v[138:141], v[50:53], v[190:193], v[138:141]
	v_mfma_f32_16x16x32_bf16 v[142:145], v[62:65], v[190:193], v[142:145]
	v_mfma_f32_16x16x32_bf16 v[122:125], v[50:53], v[198:201], v[122:125]
	v_mfma_f32_16x16x32_bf16 v[126:129], v[62:65], v[198:201], v[126:129]
	v_mfma_f32_16x16x32_bf16 v[162:165], v[66:69], v[88:91], v[162:165]
	v_mfma_f32_16x16x32_bf16 v[88:91], v[78:81], v[88:91], v[166:169]
	v_mfma_f32_16x16x32_bf16 v[162:165], v[74:77], v[92:95], v[162:165]
	v_mfma_f32_16x16x32_bf16 v[88:91], v[84:87], v[92:95], v[88:91]
	v_mfma_f32_16x16x32_bf16 v[92:95], v[66:69], v[178:181], v[146:149]
	v_mfma_f32_16x16x32_bf16 v[146:149], v[78:81], v[178:181], v[150:153]
	v_mfma_f32_16x16x32_bf16 v[130:133], v[66:69], v[186:189], v[130:133]
	v_mfma_f32_16x16x32_bf16 v[134:137], v[78:81], v[186:189], v[134:137]
	v_mfma_f32_16x16x32_bf16 v[114:117], v[66:69], v[194:197], v[114:117]
	v_mfma_f32_16x16x32_bf16 v[118:121], v[78:81], v[194:197], v[118:121]
	v_mfma_f32_16x16x32_bf16 v[150:153], v[84:87], v[182:185], v[146:149]
	v_mfma_f32_16x16x32_bf16 v[130:133], v[74:77], v[190:193], v[130:133]
	v_mfma_f32_16x16x32_bf16 v[134:137], v[84:87], v[190:193], v[134:137]
	v_mfma_f32_16x16x32_bf16 v[114:117], v[74:77], v[198:201], v[114:117]
	v_mfma_f32_16x16x32_bf16 v[118:121], v[84:87], v[198:201], v[118:121]
	v_mfma_f32_16x16x32_bf16 v[92:95], v[74:77], v[182:185], v[92:95]
	s_barrier
	s_add_i32 s20, s20, s72
	v_lshl_add_u64 v[242:243], s[12:13], 0, v[206:207]
	s_mov_b32 m0, s20
	ds_read_b128 v[146:149], v233 offset:16384
	ds_read_b128 v[166:169], v233 offset:17408
	ds_read_b128 v[178:181], v233 offset:18432
	ds_read_b128 v[182:185], v233 offset:19456
	ds_read_b128 v[186:189], v233 offset:20480
	ds_read_b128 v[190:193], v233 offset:21504
	ds_read_b128 v[194:197], v233 offset:22528
	ds_read_b128 v[198:201], v233 offset:23552
	global_load_lds_dwordx4 v[242:243], off
	s_add_i32 m0, s20, 0x2000
	s_add_u32 s20, s12, 0x80000
	v_lshl_add_u64 v[230:231], s[12:13], 0, v[210:211]
	s_addc_u32 s21, s13, 0
	s_add_i32 s23, s23, s72
	global_load_lds_dwordx4 v[230:231], off
	v_lshl_add_u64 v[8:9], s[20:21], 0, v[206:207]
	s_mov_b32 m0, s23
	v_lshl_add_u64 v[226:227], v[222:223], 0, v[204:205]
	global_load_lds_dwordx4 v[8:9], off
	v_lshl_add_u64 v[8:9], s[20:21], 0, v[210:211]
	s_add_i32 m0, s23, 0x2000
	v_lshl_add_u64 v[244:245], v[222:223], 0, v[208:209]
	global_load_lds_dwordx4 v[8:9], off
	s_mov_b32 m0, s91
	s_nop 0
	global_load_lds_dwordx4 v[226:227], off
	s_mov_b32 m0, s96
	s_nop 0
	global_load_lds_dwordx4 v[244:245], off
	s_waitcnt vmcnt(8)
	s_waitcnt lgkmcnt(0)
	s_barrier
	s_waitcnt lgkmcnt(0)
	v_mfma_f32_16x16x32_bf16 v[106:109], v[4:7], v[146:149], v[106:109]
	v_mfma_f32_16x16x32_bf16 v[110:113], v[58:61], v[146:149], v[110:113]
	v_mfma_f32_16x16x32_bf16 v[54:57], v[4:7], v[178:181], v[54:57]
	v_mfma_f32_16x16x32_bf16 v[70:73], v[58:61], v[178:181], v[70:73]
	v_mfma_f32_16x16x32_bf16 v[34:37], v[4:7], v[186:189], v[34:37]
	v_mfma_f32_16x16x32_bf16 v[38:41], v[58:61], v[186:189], v[38:41]
	v_mfma_f32_16x16x32_bf16 v[4:7], v[4:7], v[194:197], v[18:21]
	v_mfma_f32_16x16x32_bf16 v[18:21], v[58:61], v[194:197], v[22:25]
	v_mfma_f32_16x16x32_bf16 v[106:109], v[50:53], v[166:169], v[106:109]
	v_mfma_f32_16x16x32_bf16 v[110:113], v[62:65], v[166:169], v[110:113]
	v_mfma_f32_16x16x32_bf16 v[54:57], v[50:53], v[182:185], v[54:57]
	v_mfma_f32_16x16x32_bf16 v[70:73], v[62:65], v[182:185], v[70:73]
	v_mfma_f32_16x16x32_bf16 v[34:37], v[50:53], v[190:193], v[34:37]
	v_mfma_f32_16x16x32_bf16 v[38:41], v[62:65], v[190:193], v[38:41]
	v_mfma_f32_16x16x32_bf16 v[22:25], v[62:65], v[198:201], v[18:21]
	v_mfma_f32_16x16x32_bf16 v[4:7], v[50:53], v[198:201], v[4:7]
	v_mfma_f32_16x16x32_bf16 v[18:21], v[66:69], v[146:149], v[98:101]
	v_mfma_f32_16x16x32_bf16 v[50:53], v[74:77], v[166:169], v[18:21]
	v_mfma_f32_16x16x32_bf16 v[18:21], v[78:81], v[146:149], v[102:105]
	v_mfma_f32_16x16x32_bf16 v[58:61], v[84:87], v[166:169], v[18:21]
	v_mfma_f32_16x16x32_bf16 v[18:21], v[66:69], v[178:181], v[42:45]
	v_mfma_f32_16x16x32_bf16 v[42:45], v[74:77], v[182:185], v[18:21]
	v_mfma_f32_16x16x32_bf16 v[18:21], v[78:81], v[178:181], v[46:49]
	v_mfma_f32_16x16x32_bf16 v[46:49], v[84:87], v[182:185], v[18:21]
	v_mfma_f32_16x16x32_bf16 v[18:21], v[66:69], v[186:189], v[26:29]
	v_mfma_f32_16x16x32_bf16 v[26:29], v[74:77], v[190:193], v[18:21]
	v_mfma_f32_16x16x32_bf16 v[18:21], v[78:81], v[186:189], v[30:33]
	v_mfma_f32_16x16x32_bf16 v[8:11], v[66:69], v[194:197], v[10:13]
	v_mfma_f32_16x16x32_bf16 v[12:15], v[78:81], v[194:197], v[14:17]
	v_mfma_f32_16x16x32_bf16 v[30:33], v[84:87], v[190:193], v[18:21]
	v_mfma_f32_16x16x32_bf16 v[8:11], v[74:77], v[198:201], v[8:11]
	v_mfma_f32_16x16x32_bf16 v[14:17], v[84:87], v[198:201], v[12:15]
	s_barrier
	s_add_i32 s20, 0, 0x18000
	s_nop 1
	v_add_u32_e32 v12, s20, v225
	s_add_i32 s21, 0, 0x1c000
	ds_read_b128 v[18:21], v12
	ds_read_b128 v[62:65], v12 offset:1024
	ds_read_b128 v[66:69], v12 offset:2048
	ds_read_b128 v[74:77], v12 offset:3072
	v_add_u32_e32 v12, s21, v225
	ds_read_b128 v[78:81], v12
	ds_read_b128 v[84:87], v12 offset:1024
	ds_read_b128 v[178:181], v12 offset:2048
	ds_read_b128 v[182:185], v12 offset:3072
	v_lshl_add_u64 v[12:13], v[222:223], 0, s[24:25]
	s_mov_b32 m0, s97
	v_lshl_add_u64 v[104:105], v[12:13], 0, v[204:205]
	ds_read_b128 v[96:99], v233 offset:32768
	ds_read_b128 v[100:103], v233 offset:33792
	ds_read_b128 v[186:189], v233 offset:34816
	ds_read_b128 v[190:193], v233 offset:35840
	ds_read_b128 v[194:197], v233 offset:36864
	ds_read_b128 v[198:201], v233 offset:37888
	ds_read_b128 v[234:237], v233 offset:38912
	ds_read_b128 v[238:241], v233 offset:39936
	global_load_lds_dwordx4 v[104:105], off
	v_lshl_add_u64 v[12:13], v[12:13], 0, v[208:209]
	s_mov_b32 m0, s61
	s_nop 0
	global_load_lds_dwordx4 v[12:13], off
	s_waitcnt vmcnt(8)
	s_waitcnt lgkmcnt(0)
	s_barrier
	s_waitcnt lgkmcnt(0)
	v_mfma_f32_16x16x32_bf16 v[146:149], v[18:21], v[96:99], v[170:173]
	v_mfma_f32_16x16x32_bf16 v[170:173], v[62:65], v[100:103], v[146:149]
	v_mfma_f32_16x16x32_bf16 v[146:149], v[66:69], v[96:99], v[174:177]
	v_mfma_f32_16x16x32_bf16 v[174:177], v[74:77], v[100:103], v[146:149]
	v_mfma_f32_16x16x32_bf16 v[146:149], v[18:21], v[186:189], v[154:157]
	v_mfma_f32_16x16x32_bf16 v[154:157], v[62:65], v[190:193], v[146:149]
	v_mfma_f32_16x16x32_bf16 v[146:149], v[66:69], v[186:189], v[158:161]
	v_mfma_f32_16x16x32_bf16 v[138:141], v[18:21], v[194:197], v[138:141]
	v_mfma_f32_16x16x32_bf16 v[142:145], v[66:69], v[194:197], v[142:145]
	v_mfma_f32_16x16x32_bf16 v[122:125], v[18:21], v[234:237], v[122:125]
	v_mfma_f32_16x16x32_bf16 v[126:129], v[66:69], v[234:237], v[126:129]
	v_mfma_f32_16x16x32_bf16 v[158:161], v[74:77], v[190:193], v[146:149]
	v_mfma_f32_16x16x32_bf16 v[138:141], v[62:65], v[198:201], v[138:141]
	v_mfma_f32_16x16x32_bf16 v[142:145], v[74:77], v[198:201], v[142:145]
	v_mfma_f32_16x16x32_bf16 v[122:125], v[62:65], v[238:241], v[122:125]
	v_mfma_f32_16x16x32_bf16 v[126:129], v[74:77], v[238:241], v[126:129]
	v_mfma_f32_16x16x32_bf16 v[88:91], v[178:181], v[96:99], v[88:91]
	v_mfma_f32_16x16x32_bf16 v[146:149], v[78:81], v[96:99], v[162:165]
	v_mfma_f32_16x16x32_bf16 v[166:169], v[182:185], v[100:103], v[88:91]
	v_mfma_f32_16x16x32_bf16 v[88:91], v[78:81], v[186:189], v[92:95]
	v_mfma_f32_16x16x32_bf16 v[162:165], v[84:87], v[100:103], v[146:149]
	v_mfma_f32_16x16x32_bf16 v[146:149], v[84:87], v[190:193], v[88:91]
	v_mfma_f32_16x16x32_bf16 v[88:91], v[178:181], v[186:189], v[150:153]
	v_mfma_f32_16x16x32_bf16 v[150:153], v[182:185], v[190:193], v[88:91]
	v_mfma_f32_16x16x32_bf16 v[88:91], v[78:81], v[194:197], v[130:133]
	v_mfma_f32_16x16x32_bf16 v[130:133], v[84:87], v[198:201], v[88:91]
	v_mfma_f32_16x16x32_bf16 v[88:91], v[178:181], v[194:197], v[134:137]
	v_mfma_f32_16x16x32_bf16 v[134:137], v[182:185], v[198:201], v[88:91]
	v_mfma_f32_16x16x32_bf16 v[88:91], v[78:81], v[234:237], v[114:117]
	v_mfma_f32_16x16x32_bf16 v[114:117], v[84:87], v[238:241], v[88:91]
	v_mfma_f32_16x16x32_bf16 v[88:91], v[178:181], v[234:237], v[118:121]
	v_mfma_f32_16x16x32_bf16 v[118:121], v[182:185], v[238:241], v[88:91]
	s_barrier
	s_add_i32 s20, s20, s72
	v_lshl_add_u64 v[12:13], v[242:243], 0, s[68:69]
	s_mov_b32 m0, s20
	s_nop 1
	ds_read_b128 v[88:91], v233 offset:49152
	ds_read_b128 v[92:95], v233 offset:50176
	ds_read_b128 v[186:189], v233 offset:51200
	ds_read_b128 v[190:193], v233 offset:52224
	ds_read_b128 v[194:197], v233 offset:53248
	ds_read_b128 v[198:201], v233 offset:54272
	ds_read_b128 v[234:237], v233 offset:55296
	ds_read_b128 v[238:241], v233 offset:56320
	global_load_lds_dwordx4 v[12:13], off
	s_add_i32 m0, s20, 0x2000
	s_add_u32 s12, s12, 0x80080
	v_lshl_add_u64 v[12:13], v[230:231], 0, s[68:69]
	s_addc_u32 s13, s13, 0
	s_add_i32 s20, s21, s72
	global_load_lds_dwordx4 v[12:13], off
	v_lshl_add_u64 v[12:13], s[12:13], 0, v[206:207]
	s_mov_b32 m0, s20
	s_nop 0
	global_load_lds_dwordx4 v[12:13], off
	v_lshl_add_u64 v[12:13], s[12:13], 0, v[210:211]
	s_add_i32 m0, s20, 0x2000
	s_nop 0
	global_load_lds_dwordx4 v[12:13], off
	v_lshl_add_u64 v[12:13], v[226:227], 0, s[68:69]
	s_mov_b32 m0, s8
	s_nop 0
	global_load_lds_dwordx4 v[12:13], off
	v_lshl_add_u64 v[12:13], v[244:245], 0, s[68:69]
	s_mov_b32 m0, s9
	s_nop 0
	global_load_lds_dwordx4 v[12:13], off
	s_waitcnt vmcnt(8)
	s_waitcnt lgkmcnt(0)
	s_barrier
	s_waitcnt lgkmcnt(0)
	v_mfma_f32_16x16x32_bf16 v[96:99], v[18:21], v[88:91], v[106:109]
	v_mfma_f32_16x16x32_bf16 v[4:7], v[18:21], v[234:237], v[4:7]
	v_mfma_f32_16x16x32_bf16 v[106:109], v[62:65], v[92:95], v[96:99]
	v_mfma_f32_16x16x32_bf16 v[96:99], v[66:69], v[88:91], v[110:113]
	v_mfma_f32_16x16x32_bf16 v[54:57], v[18:21], v[186:189], v[54:57]
	v_mfma_f32_16x16x32_bf16 v[70:73], v[66:69], v[186:189], v[70:73]
	v_mfma_f32_16x16x32_bf16 v[34:37], v[18:21], v[194:197], v[34:37]
	v_mfma_f32_16x16x32_bf16 v[38:41], v[66:69], v[194:197], v[38:41]
	v_mfma_f32_16x16x32_bf16 v[18:21], v[62:65], v[238:241], v[4:7]
	v_mfma_f32_16x16x32_bf16 v[4:7], v[66:69], v[234:237], v[22:25]
	v_mfma_f32_16x16x32_bf16 v[110:113], v[74:77], v[92:95], v[96:99]
	v_mfma_f32_16x16x32_bf16 v[54:57], v[62:65], v[190:193], v[54:57]
	v_mfma_f32_16x16x32_bf16 v[70:73], v[74:77], v[190:193], v[70:73]
	v_mfma_f32_16x16x32_bf16 v[34:37], v[62:65], v[198:201], v[34:37]
	v_mfma_f32_16x16x32_bf16 v[38:41], v[74:77], v[198:201], v[38:41]
	v_mfma_f32_16x16x32_bf16 v[22:25], v[74:77], v[238:241], v[4:7]
	v_mfma_f32_16x16x32_bf16 v[4:7], v[78:81], v[88:91], v[50:53]
	v_mfma_f32_16x16x32_bf16 v[98:101], v[84:87], v[92:95], v[4:7]
	v_mfma_f32_16x16x32_bf16 v[4:7], v[178:181], v[88:91], v[58:61]
	v_mfma_f32_16x16x32_bf16 v[102:105], v[182:185], v[92:95], v[4:7]
	v_mfma_f32_16x16x32_bf16 v[4:7], v[78:81], v[186:189], v[42:45]
	v_mfma_f32_16x16x32_bf16 v[42:45], v[84:87], v[190:193], v[4:7]
	v_mfma_f32_16x16x32_bf16 v[4:7], v[178:181], v[186:189], v[46:49]
	v_mfma_f32_16x16x32_bf16 v[46:49], v[182:185], v[190:193], v[4:7]
	v_mfma_f32_16x16x32_bf16 v[4:7], v[78:81], v[194:197], v[26:29]
	v_mfma_f32_16x16x32_bf16 v[26:29], v[84:87], v[198:201], v[4:7]
	v_mfma_f32_16x16x32_bf16 v[4:7], v[178:181], v[194:197], v[30:33]
	v_mfma_f32_16x16x32_bf16 v[30:33], v[182:185], v[198:201], v[4:7]
	v_mfma_f32_16x16x32_bf16 v[4:7], v[78:81], v[234:237], v[8:11]
	v_mfma_f32_16x16x32_bf16 v[10:13], v[84:87], v[238:241], v[4:7]
	v_mfma_f32_16x16x32_bf16 v[4:7], v[178:181], v[234:237], v[14:17]
	v_mfma_f32_16x16x32_bf16 v[14:17], v[182:185], v[238:241], v[4:7]
	s_barrier
	s_add_i32 s19, s19, 2
	s_add_u32 s16, s16, 0x100
	s_addc_u32 s17, s17, 0
	s_mov_b64 s[12:13], 0x100
	s_cmp_gt_u32 s19, 29
	v_lshl_add_u64 v[2:3], v[2:3], 0, s[12:13]
	s_cbranch_scc0 .LBB0_1290
	s_and_b64 vcc, exec, s[36:37]
	s_cbranch_vccz .LBB0_1293
	s_barrier

.LBB0_1618:
	s_add_i32 s89, s38, 2
	s_add_u32 s36, s34, 0x100
	s_addc_u32 s37, s35, 0
	s_add_i32 s90, 0, 0x10000
	s_cmp_eq_u32 s76, s38
	s_cselect_b32 s41, s29, s37
	s_cselect_b32 s40, s28, s36
	s_cselect_b32 s39, s31, s88
	s_cselect_b32 s38, s30, s87
	s_add_i32 s91, 0, 0x14000
	v_add_u32_e32 v144, s90, v201
	v_add_u32_e32 v160, s91, v201
	ds_read_b128 v[132:135], v144
	ds_read_b128 v[136:139], v144 offset:1024
	ds_read_b128 v[140:143], v144 offset:2048
	ds_read_b128 v[144:147], v144 offset:3072
	ds_read_b128 v[148:151], v160
	ds_read_b128 v[152:155], v160 offset:1024
	ds_read_b128 v[156:159], v160 offset:2048
	ds_read_b128 v[160:163], v160 offset:3072
	v_lshl_add_u64 v[198:199], s[34:35], 0, v[172:173]
	s_add_i32 m0, s60, 0xc000
	ds_read_b128 v[174:177], v202
	ds_read_b128 v[178:181], v202 offset:1024
	ds_read_b128 v[182:185], v202 offset:2048
	ds_read_b128 v[186:189], v202 offset:3072
	ds_read_b128 v[190:193], v202 offset:4096
	ds_read_b128 v[194:197], v202 offset:5120
	ds_read_b128 v[204:207], v202 offset:6144
	ds_read_b128 v[208:211], v202 offset:7168
	global_load_lds_dwordx4 v[198:199], off
	v_lshl_add_u64 v[198:199], s[34:35], 0, v[170:171]
	s_add_i32 m0, s60, 0xe000
	s_nop 0
	global_load_lds_dwordx4 v[198:199], off
	s_waitcnt vmcnt(8)
	s_waitcnt lgkmcnt(0)
	s_barrier
	s_waitcnt lgkmcnt(0)
	v_mfma_f32_16x16x32_bf16 v[128:131], v[132:135], v[174:177], v[128:131]
	v_mfma_f32_16x16x32_bf16 v[124:127], v[140:143], v[174:177], v[124:127]
	v_mfma_f32_16x16x32_bf16 v[120:123], v[132:135], v[182:185], v[120:123]
	v_mfma_f32_16x16x32_bf16 v[116:119], v[140:143], v[182:185], v[116:119]
	v_mfma_f32_16x16x32_bf16 v[108:111], v[132:135], v[190:193], v[108:111]
	v_mfma_f32_16x16x32_bf16 v[100:103], v[140:143], v[190:193], v[100:103]
	v_mfma_f32_16x16x32_bf16 v[92:95], v[132:135], v[204:207], v[92:95]
	v_mfma_f32_16x16x32_bf16 v[84:87], v[140:143], v[204:207], v[84:87]
	v_mfma_f32_16x16x32_bf16 v[128:131], v[136:139], v[178:181], v[128:131]
	v_mfma_f32_16x16x32_bf16 v[124:127], v[144:147], v[178:181], v[124:127]
	v_mfma_f32_16x16x32_bf16 v[120:123], v[136:139], v[186:189], v[120:123]
	v_mfma_f32_16x16x32_bf16 v[116:119], v[144:147], v[186:189], v[116:119]
	v_mfma_f32_16x16x32_bf16 v[108:111], v[136:139], v[194:197], v[108:111]
	v_mfma_f32_16x16x32_bf16 v[100:103], v[144:147], v[194:197], v[100:103]
	v_mfma_f32_16x16x32_bf16 v[92:95], v[136:139], v[208:211], v[92:95]
	v_mfma_f32_16x16x32_bf16 v[84:87], v[144:147], v[208:211], v[84:87]
	v_mfma_f32_16x16x32_bf16 v[112:115], v[148:151], v[174:177], v[112:115]
	v_mfma_f32_16x16x32_bf16 v[104:107], v[156:159], v[174:177], v[104:107]
	v_mfma_f32_16x16x32_bf16 v[96:99], v[148:151], v[182:185], v[96:99]
	v_mfma_f32_16x16x32_bf16 v[88:91], v[156:159], v[182:185], v[88:91]
	v_mfma_f32_16x16x32_bf16 v[78:81], v[148:151], v[190:193], v[78:81]
	v_mfma_f32_16x16x32_bf16 v[74:77], v[156:159], v[190:193], v[74:77]
	v_mfma_f32_16x16x32_bf16 v[70:73], v[148:151], v[204:207], v[70:73]
	v_mfma_f32_16x16x32_bf16 v[66:69], v[156:159], v[204:207], v[66:69]
	v_mfma_f32_16x16x32_bf16 v[112:115], v[152:155], v[178:181], v[112:115]
	v_mfma_f32_16x16x32_bf16 v[104:107], v[160:163], v[178:181], v[104:107]
	v_mfma_f32_16x16x32_bf16 v[96:99], v[152:155], v[186:189], v[96:99]
	v_mfma_f32_16x16x32_bf16 v[88:91], v[160:163], v[186:189], v[88:91]
	v_mfma_f32_16x16x32_bf16 v[78:81], v[152:155], v[194:197], v[78:81]
	v_mfma_f32_16x16x32_bf16 v[74:77], v[160:163], v[194:197], v[74:77]
	v_mfma_f32_16x16x32_bf16 v[70:73], v[152:155], v[208:211], v[70:73]
	v_mfma_f32_16x16x32_bf16 v[66:69], v[160:163], v[208:211], v[66:69]
	s_barrier
	s_add_i32 s34, s90, s58
	v_lshl_add_u64 v[198:199], s[38:39], 0, v[82:83]
	s_mov_b32 m0, s34
	ds_read_b128 v[174:177], v202 offset:16384
	ds_read_b128 v[178:181], v202 offset:17408
	ds_read_b128 v[182:185], v202 offset:18432
	ds_read_b128 v[186:189], v202 offset:19456
	ds_read_b128 v[190:193], v202 offset:20480
	ds_read_b128 v[194:197], v202 offset:21504
	ds_read_b128 v[204:207], v202 offset:22528
	ds_read_b128 v[208:211], v202 offset:23552
	global_load_lds_dwordx4 v[198:199], off
	s_add_i32 m0, s34, 0x2000
	s_add_u32 s34, s38, 0x160000
	v_lshl_add_u64 v[212:213], s[38:39], 0, v[168:169]
	s_addc_u32 s35, s39, 0
	s_add_i32 s90, s91, s58
	global_load_lds_dwordx4 v[212:213], off
	v_lshl_add_u64 v[214:215], s[34:35], 0, v[82:83]
	s_mov_b32 m0, s90
	v_lshl_add_u64 v[216:217], s[40:41], 0, v[166:167]
	global_load_lds_dwordx4 v[214:215], off
	v_lshl_add_u64 v[214:215], s[34:35], 0, v[168:169]
	s_add_i32 m0, s90, 0x2000
	s_nop 0
	global_load_lds_dwordx4 v[214:215], off
	v_lshl_add_u64 v[214:215], s[40:41], 0, v[164:165]
	s_mov_b32 m0, s60
	s_nop 0
	global_load_lds_dwordx4 v[214:215], off
	s_mov_b32 m0, s61
	s_nop 0
	global_load_lds_dwordx4 v[216:217], off
	s_waitcnt vmcnt(8)
	s_waitcnt lgkmcnt(0)
	s_barrier
	s_waitcnt lgkmcnt(0)
	v_mfma_f32_16x16x32_bf16 v[62:65], v[132:135], v[174:177], v[62:65]
	v_mfma_f32_16x16x32_bf16 v[58:61], v[140:143], v[174:177], v[58:61]
	v_mfma_f32_16x16x32_bf16 v[54:57], v[132:135], v[182:185], v[54:57]
	v_mfma_f32_16x16x32_bf16 v[50:53], v[140:143], v[182:185], v[50:53]
	v_mfma_f32_16x16x32_bf16 v[38:41], v[132:135], v[190:193], v[38:41]
	v_mfma_f32_16x16x32_bf16 v[34:37], v[140:143], v[190:193], v[34:37]
	v_mfma_f32_16x16x32_bf16 v[22:25], v[132:135], v[204:207], v[22:25]
	v_mfma_f32_16x16x32_bf16 v[18:21], v[140:143], v[204:207], v[18:21]
	v_mfma_f32_16x16x32_bf16 v[62:65], v[136:139], v[178:181], v[62:65]
	v_mfma_f32_16x16x32_bf16 v[58:61], v[144:147], v[178:181], v[58:61]
	v_mfma_f32_16x16x32_bf16 v[54:57], v[136:139], v[186:189], v[54:57]
	v_mfma_f32_16x16x32_bf16 v[50:53], v[144:147], v[186:189], v[50:53]
	v_mfma_f32_16x16x32_bf16 v[38:41], v[136:139], v[194:197], v[38:41]
	v_mfma_f32_16x16x32_bf16 v[34:37], v[144:147], v[194:197], v[34:37]
	v_mfma_f32_16x16x32_bf16 v[22:25], v[136:139], v[208:211], v[22:25]
	v_mfma_f32_16x16x32_bf16 v[18:21], v[144:147], v[208:211], v[18:21]
	v_mfma_f32_16x16x32_bf16 v[46:49], v[148:151], v[174:177], v[46:49]
	v_mfma_f32_16x16x32_bf16 v[42:45], v[156:159], v[174:177], v[42:45]
	v_mfma_f32_16x16x32_bf16 v[30:33], v[148:151], v[182:185], v[30:33]
	v_mfma_f32_16x16x32_bf16 v[26:29], v[156:159], v[182:185], v[26:29]
	v_mfma_f32_16x16x32_bf16 v[14:17], v[148:151], v[190:193], v[14:17]
	v_mfma_f32_16x16x32_bf16 v[10:13], v[156:159], v[190:193], v[10:13]
	v_mfma_f32_16x16x32_bf16 v[6:9], v[148:151], v[204:207], v[6:9]
	v_mfma_f32_16x16x32_bf16 v[2:5], v[156:159], v[204:207], v[2:5]
	v_mfma_f32_16x16x32_bf16 v[46:49], v[152:155], v[178:181], v[46:49]
	v_mfma_f32_16x16x32_bf16 v[42:45], v[160:163], v[178:181], v[42:45]
	v_mfma_f32_16x16x32_bf16 v[30:33], v[152:155], v[186:189], v[30:33]
	v_mfma_f32_16x16x32_bf16 v[26:29], v[160:163], v[186:189], v[26:29]
	v_mfma_f32_16x16x32_bf16 v[14:17], v[152:155], v[194:197], v[14:17]
	v_mfma_f32_16x16x32_bf16 v[10:13], v[160:163], v[194:197], v[10:13]
	v_mfma_f32_16x16x32_bf16 v[6:9], v[152:155], v[208:211], v[6:9]
	v_mfma_f32_16x16x32_bf16 v[2:5], v[160:163], v[208:211], v[2:5]
	s_barrier
	s_add_i32 s90, 0, 0x18000
	s_add_i32 s91, 0, 0x1c000
	v_add_u32_e32 v144, s90, v201
	v_add_u32_e32 v160, s91, v201
	ds_read_b128 v[132:135], v144
	ds_read_b128 v[136:139], v144 offset:1024
	ds_read_b128 v[140:143], v144 offset:2048
	ds_read_b128 v[144:147], v144 offset:3072
	ds_read_b128 v[148:151], v160
	ds_read_b128 v[152:155], v160 offset:1024
	ds_read_b128 v[156:159], v160 offset:2048
	ds_read_b128 v[160:163], v160 offset:3072
	s_add_u32 s34, s40, 0x160000
	s_addc_u32 s35, s41, 0
	s_mov_b32 m0, s62
	v_lshl_add_u64 v[218:219], s[34:35], 0, v[164:165]
	ds_read_b128 v[174:177], v202 offset:32768
	ds_read_b128 v[178:181], v202 offset:33792
	ds_read_b128 v[182:185], v202 offset:34816
	ds_read_b128 v[186:189], v202 offset:35840
	ds_read_b128 v[190:193], v202 offset:36864
	ds_read_b128 v[194:197], v202 offset:37888
	ds_read_b128 v[204:207], v202 offset:38912
	ds_read_b128 v[208:211], v202 offset:39936
	global_load_lds_dwordx4 v[218:219], off
	v_lshl_add_u64 v[218:219], s[34:35], 0, v[166:167]
	s_mov_b32 m0, s63
	s_nop 0
	global_load_lds_dwordx4 v[218:219], off
	s_waitcnt vmcnt(8)
	s_waitcnt lgkmcnt(0)
	s_barrier
	s_waitcnt lgkmcnt(0)
	v_mfma_f32_16x16x32_bf16 v[128:131], v[132:135], v[174:177], v[128:131]
	v_mfma_f32_16x16x32_bf16 v[124:127], v[140:143], v[174:177], v[124:127]
	v_mfma_f32_16x16x32_bf16 v[120:123], v[132:135], v[182:185], v[120:123]
	v_mfma_f32_16x16x32_bf16 v[116:119], v[140:143], v[182:185], v[116:119]
	v_mfma_f32_16x16x32_bf16 v[108:111], v[132:135], v[190:193], v[108:111]
	v_mfma_f32_16x16x32_bf16 v[100:103], v[140:143], v[190:193], v[100:103]
	v_mfma_f32_16x16x32_bf16 v[92:95], v[132:135], v[204:207], v[92:95]
	v_mfma_f32_16x16x32_bf16 v[84:87], v[140:143], v[204:207], v[84:87]
	v_mfma_f32_16x16x32_bf16 v[128:131], v[136:139], v[178:181], v[128:131]
	v_mfma_f32_16x16x32_bf16 v[124:127], v[144:147], v[178:181], v[124:127]
	v_mfma_f32_16x16x32_bf16 v[120:123], v[136:139], v[186:189], v[120:123]
	v_mfma_f32_16x16x32_bf16 v[116:119], v[144:147], v[186:189], v[116:119]
	v_mfma_f32_16x16x32_bf16 v[108:111], v[136:139], v[194:197], v[108:111]
	v_mfma_f32_16x16x32_bf16 v[100:103], v[144:147], v[194:197], v[100:103]
	v_mfma_f32_16x16x32_bf16 v[92:95], v[136:139], v[208:211], v[92:95]
	v_mfma_f32_16x16x32_bf16 v[84:87], v[144:147], v[208:211], v[84:87]
	v_mfma_f32_16x16x32_bf16 v[112:115], v[148:151], v[174:177], v[112:115]
	v_mfma_f32_16x16x32_bf16 v[104:107], v[156:159], v[174:177], v[104:107]
	v_mfma_f32_16x16x32_bf16 v[96:99], v[148:151], v[182:185], v[96:99]
	v_mfma_f32_16x16x32_bf16 v[88:91], v[156:159], v[182:185], v[88:91]
	v_mfma_f32_16x16x32_bf16 v[78:81], v[148:151], v[190:193], v[78:81]
	v_mfma_f32_16x16x32_bf16 v[74:77], v[156:159], v[190:193], v[74:77]
	v_mfma_f32_16x16x32_bf16 v[70:73], v[148:151], v[204:207], v[70:73]
	v_mfma_f32_16x16x32_bf16 v[66:69], v[156:159], v[204:207], v[66:69]
	v_mfma_f32_16x16x32_bf16 v[112:115], v[152:155], v[178:181], v[112:115]
	v_mfma_f32_16x16x32_bf16 v[104:107], v[160:163], v[178:181], v[104:107]
	v_mfma_f32_16x16x32_bf16 v[96:99], v[152:155], v[186:189], v[96:99]
	v_mfma_f32_16x16x32_bf16 v[88:91], v[160:163], v[186:189], v[88:91]
	v_mfma_f32_16x16x32_bf16 v[78:81], v[152:155], v[194:197], v[78:81]
	v_mfma_f32_16x16x32_bf16 v[74:77], v[160:163], v[194:197], v[74:77]
	v_mfma_f32_16x16x32_bf16 v[70:73], v[152:155], v[208:211], v[70:73]
	v_mfma_f32_16x16x32_bf16 v[66:69], v[160:163], v[208:211], v[66:69]
	s_barrier
	s_add_i32 s34, s90, s58
	v_lshl_add_u64 v[198:199], v[198:199], 0, s[68:69]
	s_mov_b32 m0, s34
	ds_read_b128 v[174:177], v202 offset:49152
	ds_read_b128 v[178:181], v202 offset:50176
	ds_read_b128 v[182:185], v202 offset:51200
	ds_read_b128 v[186:189], v202 offset:52224
	ds_read_b128 v[190:193], v202 offset:53248
	ds_read_b128 v[194:197], v202 offset:54272
	ds_read_b128 v[204:207], v202 offset:55296
	ds_read_b128 v[208:211], v202 offset:56320
	global_load_lds_dwordx4 v[198:199], off
	s_add_i32 m0, s34, 0x2000
	s_add_u32 s34, s38, 0x160080
	v_lshl_add_u64 v[198:199], v[212:213], 0, s[68:69]
	s_addc_u32 s35, s39, 0
	s_add_i32 s38, s91, s58
	global_load_lds_dwordx4 v[198:199], off
	v_lshl_add_u64 v[198:199], s[34:35], 0, v[82:83]
	s_mov_b32 m0, s38
	s_nop 0
	global_load_lds_dwordx4 v[198:199], off
	v_lshl_add_u64 v[198:199], s[34:35], 0, v[168:169]
	s_add_i32 m0, s38, 0x2000
	s_nop 0
	global_load_lds_dwordx4 v[198:199], off
	v_lshl_add_u64 v[198:199], v[214:215], 0, s[68:69]
	s_mov_b32 m0, s74
	s_nop 0
	global_load_lds_dwordx4 v[198:199], off
	v_lshl_add_u64 v[198:199], v[216:217], 0, s[68:69]
	s_mov_b32 m0, s75
	s_nop 0
	global_load_lds_dwordx4 v[198:199], off
	s_waitcnt vmcnt(8)
	s_waitcnt lgkmcnt(0)
	s_barrier
	s_waitcnt lgkmcnt(0)
	v_mfma_f32_16x16x32_bf16 v[62:65], v[132:135], v[174:177], v[62:65]
	v_mfma_f32_16x16x32_bf16 v[58:61], v[140:143], v[174:177], v[58:61]
	v_mfma_f32_16x16x32_bf16 v[54:57], v[132:135], v[182:185], v[54:57]
	v_mfma_f32_16x16x32_bf16 v[50:53], v[140:143], v[182:185], v[50:53]
	v_mfma_f32_16x16x32_bf16 v[38:41], v[132:135], v[190:193], v[38:41]
	v_mfma_f32_16x16x32_bf16 v[34:37], v[140:143], v[190:193], v[34:37]
	v_mfma_f32_16x16x32_bf16 v[22:25], v[132:135], v[204:207], v[22:25]
	v_mfma_f32_16x16x32_bf16 v[18:21], v[140:143], v[204:207], v[18:21]
	v_mfma_f32_16x16x32_bf16 v[62:65], v[136:139], v[178:181], v[62:65]
	v_mfma_f32_16x16x32_bf16 v[58:61], v[144:147], v[178:181], v[58:61]
	v_mfma_f32_16x16x32_bf16 v[54:57], v[136:139], v[186:189], v[54:57]
	v_mfma_f32_16x16x32_bf16 v[50:53], v[144:147], v[186:189], v[50:53]
	v_mfma_f32_16x16x32_bf16 v[38:41], v[136:139], v[194:197], v[38:41]
	v_mfma_f32_16x16x32_bf16 v[34:37], v[144:147], v[194:197], v[34:37]
	v_mfma_f32_16x16x32_bf16 v[22:25], v[136:139], v[208:211], v[22:25]
	v_mfma_f32_16x16x32_bf16 v[18:21], v[144:147], v[208:211], v[18:21]
	v_mfma_f32_16x16x32_bf16 v[46:49], v[148:151], v[174:177], v[46:49]
	v_mfma_f32_16x16x32_bf16 v[42:45], v[156:159], v[174:177], v[42:45]
	v_mfma_f32_16x16x32_bf16 v[30:33], v[148:151], v[182:185], v[30:33]
	v_mfma_f32_16x16x32_bf16 v[26:29], v[156:159], v[182:185], v[26:29]
	v_mfma_f32_16x16x32_bf16 v[14:17], v[148:151], v[190:193], v[14:17]
	v_mfma_f32_16x16x32_bf16 v[10:13], v[156:159], v[190:193], v[10:13]
	v_mfma_f32_16x16x32_bf16 v[6:9], v[148:151], v[204:207], v[6:9]
	v_mfma_f32_16x16x32_bf16 v[2:5], v[156:159], v[204:207], v[2:5]
	v_mfma_f32_16x16x32_bf16 v[46:49], v[152:155], v[178:181], v[46:49]
	v_mfma_f32_16x16x32_bf16 v[42:45], v[160:163], v[178:181], v[42:45]
	v_mfma_f32_16x16x32_bf16 v[30:33], v[152:155], v[186:189], v[30:33]
	v_mfma_f32_16x16x32_bf16 v[26:29], v[160:163], v[186:189], v[26:29]
	v_mfma_f32_16x16x32_bf16 v[14:17], v[152:155], v[194:197], v[14:17]
	v_mfma_f32_16x16x32_bf16 v[10:13], v[160:163], v[194:197], v[10:13]
	v_mfma_f32_16x16x32_bf16 v[6:9], v[152:155], v[208:211], v[6:9]
	v_mfma_f32_16x16x32_bf16 v[2:5], v[160:163], v[208:211], v[2:5]
	s_barrier
	s_add_u32 s87, s87, 0x100
	s_addc_u32 s88, s88, 0
	s_cmp_ge_u32 s89, s64
	s_mov_b64 s[34:35], s[36:37]
	s_mov_b32 s38, s89
	s_cbranch_scc0 .LBB0_1618
	s_and_b64 vcc, exec, s[24:25]
	s_cbranch_vccz .LBB0_1621
	s_barrier
